# rolling 32-deep load window in the adaLN modulation GEMV (on top of fused S1 scan, rcp epilogues, attention nop trimming)
# speedup vs baseline: 1.0454x; 1.0015x over previous
; #define LAS __attribute__((address_space(3)))
; __device__ __forceinline__ void mod_item(int item, const float* w_ada, const float* b_ada, float* mod, LAS unsigned char* lds, int tid) {
;     const int layer = item / 96, col0 = (item % 96) * 64, quad = tid & 15, ks = tid >> 4;
;     const LAS float* cond = (const LAS float*)lds; LAS float* red = (LAS float*)(lds + 65536);
;     const float* wp = w_ada + ((size_t)layer * 2048 + ks * 64) * 6144 + col0 + quad * 4;
;     f32x4 a0 = {0, 0, 0, 0}, a1 = a0, a2 = a0, a3 = a0, a4 = a0, a5 = a0, a6 = a0, a7 = a0;
; #pragma unroll 8
;     for (int kk = 0; kk < 64; ++kk) {
;         const f32x4 w = *(const f32x4*)(wp + (size_t)kk * 6144);
;         const f32x4 c0 = *(const LAS f32x4*)(cond + (ks * 64 + kk) * 8), c1 = *(const LAS f32x4*)(cond + (ks * 64 + kk) * 8 + 4);
;         a0 += c0[0] * w; a1 += c0[1] * w; a2 += c0[2] * w; a3 += c0[3] * w; a4 += c1[0] * w; a5 += c1[1] * w; a6 += c1[2] * w; a7 += c1[3] * w;
;     }
;     LAS float* rp = red + (ks * 8) * 64 + quad * 4;
;     *(LAS f32x4*)(rp + 0 * 64) = a0; *(LAS f32x4*)(rp + 1 * 64) = a1; *(LAS f32x4*)(rp + 2 * 64) = a2; *(LAS f32x4*)(rp + 3 * 64) = a3;
;     *(LAS f32x4*)(rp + 4 * 64) = a4; *(LAS f32x4*)(rp + 5 * 64) = a5; *(LAS f32x4*)(rp + 6 * 64) = a6; *(LAS f32x4*)(rp + 7 * 64) = a7;
;     __syncthreads();
;     { const int b = tid >> 6, col = tid & 63; float s = 0.f;
; #pragma unroll 8
;       for (int k2 = 0; k2 < 32; ++k2) s += red[(k2 * 8 + b) * 64 + col];
;       mod[((size_t)layer * 8 + b) * 6144 + col0 + col] = s + b_ada[(size_t)layer * 6144 + col0 + col]; }
;     __syncthreads();
; }
.LBB0_16:
	s_mov_b32 s36, 0x6000
	s_mov_b32 s37, 0
	v_mov_b32_e32 v74, v72
	v_mov_b32_e32 v75, v73
	ds_read_b128 v[144:147], v78
	ds_read_b128 v[148:151], v78 offset:16
	global_load_dwordx4 v[34:37], v[74:75], off
	v_lshl_add_u64 v[74:75], v[74:75], 0, s[36:37]
	global_load_dwordx4 v[38:41], v[74:75], off
	v_lshl_add_u64 v[74:75], v[74:75], 0, s[36:37]
	global_load_dwordx4 v[42:45], v[74:75], off
	v_lshl_add_u64 v[74:75], v[74:75], 0, s[36:37]
	global_load_dwordx4 v[46:49], v[74:75], off
	v_lshl_add_u64 v[74:75], v[74:75], 0, s[36:37]
	global_load_dwordx4 v[50:53], v[74:75], off
	v_lshl_add_u64 v[74:75], v[74:75], 0, s[36:37]
	global_load_dwordx4 v[54:57], v[74:75], off
	v_lshl_add_u64 v[74:75], v[74:75], 0, s[36:37]
	global_load_dwordx4 v[58:61], v[74:75], off
	v_lshl_add_u64 v[74:75], v[74:75], 0, s[36:37]
	global_load_dwordx4 v[62:65], v[74:75], off
	v_lshl_add_u64 v[74:75], v[74:75], 0, s[36:37]
	global_load_dwordx4 v[80:83], v[74:75], off
	v_lshl_add_u64 v[74:75], v[74:75], 0, s[36:37]
	global_load_dwordx4 v[84:87], v[74:75], off
	v_lshl_add_u64 v[74:75], v[74:75], 0, s[36:37]
	global_load_dwordx4 v[88:91], v[74:75], off
	v_lshl_add_u64 v[74:75], v[74:75], 0, s[36:37]
	global_load_dwordx4 v[92:95], v[74:75], off
	v_lshl_add_u64 v[74:75], v[74:75], 0, s[36:37]
	global_load_dwordx4 v[96:99], v[74:75], off
	v_lshl_add_u64 v[74:75], v[74:75], 0, s[36:37]
	global_load_dwordx4 v[100:103], v[74:75], off
	v_lshl_add_u64 v[74:75], v[74:75], 0, s[36:37]
	global_load_dwordx4 v[104:107], v[74:75], off
	v_lshl_add_u64 v[74:75], v[74:75], 0, s[36:37]
	global_load_dwordx4 v[108:111], v[74:75], off
	v_lshl_add_u64 v[74:75], v[74:75], 0, s[36:37]
	global_load_dwordx4 v[112:115], v[74:75], off
	v_lshl_add_u64 v[74:75], v[74:75], 0, s[36:37]
	global_load_dwordx4 v[116:119], v[74:75], off
	v_lshl_add_u64 v[74:75], v[74:75], 0, s[36:37]
	global_load_dwordx4 v[120:123], v[74:75], off
	v_lshl_add_u64 v[74:75], v[74:75], 0, s[36:37]
	global_load_dwordx4 v[124:127], v[74:75], off
	v_lshl_add_u64 v[74:75], v[74:75], 0, s[36:37]
	global_load_dwordx4 v[128:131], v[74:75], off
	v_lshl_add_u64 v[74:75], v[74:75], 0, s[36:37]
	global_load_dwordx4 v[132:135], v[74:75], off
	v_lshl_add_u64 v[74:75], v[74:75], 0, s[36:37]
	global_load_dwordx4 v[136:139], v[74:75], off
	v_lshl_add_u64 v[74:75], v[74:75], 0, s[36:37]
	global_load_dwordx4 v[140:143], v[74:75], off
	v_lshl_add_u64 v[74:75], v[74:75], 0, s[36:37]
	global_load_dwordx4 v[176:179], v[74:75], off
	v_lshl_add_u64 v[74:75], v[74:75], 0, s[36:37]
	global_load_dwordx4 v[180:183], v[74:75], off
	v_lshl_add_u64 v[74:75], v[74:75], 0, s[36:37]
	global_load_dwordx4 v[184:187], v[74:75], off
	v_lshl_add_u64 v[74:75], v[74:75], 0, s[36:37]
	global_load_dwordx4 v[188:191], v[74:75], off
	v_lshl_add_u64 v[74:75], v[74:75], 0, s[36:37]
	global_load_dwordx4 v[192:195], v[74:75], off
	v_lshl_add_u64 v[74:75], v[74:75], 0, s[36:37]
	global_load_dwordx4 v[196:199], v[74:75], off
	v_lshl_add_u64 v[74:75], v[74:75], 0, s[36:37]
	global_load_dwordx4 v[200:203], v[74:75], off
	v_lshl_add_u64 v[74:75], v[74:75], 0, s[36:37]
	global_load_dwordx4 v[204:207], v[74:75], off
	v_lshl_add_u64 v[74:75], v[74:75], 0, s[36:37]
	s_waitcnt lgkmcnt(0)
	ds_read_b128 v[152:155], v78 offset:32
	ds_read_b128 v[156:159], v78 offset:48
	s_waitcnt vmcnt(31)
	v_pk_fma_f32 v[2:3], v[34:35], v[144:145], v[2:3] op_sel_hi:[1,0,1]
	v_pk_fma_f32 v[4:5], v[36:37], v[144:145], v[4:5] op_sel_hi:[1,0,1]
	v_pk_fma_f32 v[10:11], v[34:35], v[144:145], v[10:11] op_sel:[0,1,0]
	v_pk_fma_f32 v[12:13], v[36:37], v[144:145], v[12:13] op_sel:[0,1,0]
	v_pk_fma_f32 v[14:15], v[34:35], v[146:147], v[14:15] op_sel_hi:[1,0,1]
	v_pk_fma_f32 v[16:17], v[36:37], v[146:147], v[16:17] op_sel_hi:[1,0,1]
	v_pk_fma_f32 v[6:7], v[34:35], v[146:147], v[6:7] op_sel:[0,1,0]
	v_pk_fma_f32 v[8:9], v[36:37], v[146:147], v[8:9] op_sel:[0,1,0]
	v_pk_fma_f32 v[18:19], v[34:35], v[148:149], v[18:19] op_sel_hi:[1,0,1]
	v_pk_fma_f32 v[20:21], v[36:37], v[148:149], v[20:21] op_sel_hi:[1,0,1]
	v_pk_fma_f32 v[26:27], v[34:35], v[148:149], v[26:27] op_sel:[0,1,0]
	v_pk_fma_f32 v[28:29], v[36:37], v[148:149], v[28:29] op_sel:[0,1,0]
	v_pk_fma_f32 v[30:31], v[34:35], v[150:151], v[30:31] op_sel_hi:[1,0,1]
	v_pk_fma_f32 v[32:33], v[36:37], v[150:151], v[32:33] op_sel_hi:[1,0,1]
	v_pk_fma_f32 v[22:23], v[34:35], v[150:151], v[22:23] op_sel:[0,1,0]
	v_pk_fma_f32 v[24:25], v[36:37], v[150:151], v[24:25] op_sel:[0,1,0]
	global_load_dwordx4 v[34:37], v[74:75], off
	v_lshl_add_u64 v[74:75], v[74:75], 0, s[36:37]
	s_waitcnt lgkmcnt(0)
	ds_read_b128 v[144:147], v78 offset:64
	ds_read_b128 v[148:151], v78 offset:80
	s_waitcnt vmcnt(31)
	v_pk_fma_f32 v[2:3], v[38:39], v[152:153], v[2:3] op_sel_hi:[1,0,1]
	v_pk_fma_f32 v[4:5], v[40:41], v[152:153], v[4:5] op_sel_hi:[1,0,1]
	v_pk_fma_f32 v[10:11], v[38:39], v[152:153], v[10:11] op_sel:[0,1,0]
	v_pk_fma_f32 v[12:13], v[40:41], v[152:153], v[12:13] op_sel:[0,1,0]
	v_pk_fma_f32 v[14:15], v[38:39], v[154:155], v[14:15] op_sel_hi:[1,0,1]
	v_pk_fma_f32 v[16:17], v[40:41], v[154:155], v[16:17] op_sel_hi:[1,0,1]
	v_pk_fma_f32 v[6:7], v[38:39], v[154:155], v[6:7] op_sel:[0,1,0]
	v_pk_fma_f32 v[8:9], v[40:41], v[154:155], v[8:9] op_sel:[0,1,0]
	v_pk_fma_f32 v[18:19], v[38:39], v[156:157], v[18:19] op_sel_hi:[1,0,1]
	v_pk_fma_f32 v[20:21], v[40:41], v[156:157], v[20:21] op_sel_hi:[1,0,1]
	v_pk_fma_f32 v[26:27], v[38:39], v[156:157], v[26:27] op_sel:[0,1,0]
	v_pk_fma_f32 v[28:29], v[40:41], v[156:157], v[28:29] op_sel:[0,1,0]
	v_pk_fma_f32 v[30:31], v[38:39], v[158:159], v[30:31] op_sel_hi:[1,0,1]
	v_pk_fma_f32 v[32:33], v[40:41], v[158:159], v[32:33] op_sel_hi:[1,0,1]
	v_pk_fma_f32 v[22:23], v[38:39], v[158:159], v[22:23] op_sel:[0,1,0]
	v_pk_fma_f32 v[24:25], v[40:41], v[158:159], v[24:25] op_sel:[0,1,0]
	global_load_dwordx4 v[38:41], v[74:75], off
	v_lshl_add_u64 v[74:75], v[74:75], 0, s[36:37]
	s_waitcnt lgkmcnt(0)
; #define LAS __attribute__((address_space(3)))
; __device__ __forceinline__ void mod_item(int item, const float* w_ada, const float* b_ada, float* mod, LAS unsigned char* lds, int tid) {
;     ...
;     const float* wp = w_ada + ((size_t)layer * 2048 + ks * 64) * 6144 + col0 + quad * 4;
;     f32x4 a0 = {0, 0, 0, 0}, a1 = a0, a2 = a0, a3 = a0, a4 = a0, a5 = a0, a6 = a0, a7 = a0;
; #pragma unroll 8
;     for (int kk = 0; kk < 64; ++kk) {
;         const f32x4 w = *(const f32x4*)(wp + (size_t)kk * 6144);
;         const f32x4 c0 = *(const LAS f32x4*)(cond + (ks * 64 + kk) * 8), c1 = *(const LAS f32x4*)(cond + (ks * 64 + kk) * 8 + 4);
;         a0 += c0[0] * w; a1 += c0[1] * w; a2 += c0[2] * w; a3 += c0[3] * w; a4 += c1[0] * w; a5 += c1[1] * w; a6 += c1[2] * w; a7 += c1[3] * w;
;     }
	ds_read_b128 v[152:155], v78 offset:96
	ds_read_b128 v[156:159], v78 offset:112
	s_waitcnt vmcnt(31)
	v_pk_fma_f32 v[2:3], v[42:43], v[144:145], v[2:3] op_sel_hi:[1,0,1]
	v_pk_fma_f32 v[4:5], v[44:45], v[144:145], v[4:5] op_sel_hi:[1,0,1]
	v_pk_fma_f32 v[10:11], v[42:43], v[144:145], v[10:11] op_sel:[0,1,0]
	v_pk_fma_f32 v[12:13], v[44:45], v[144:145], v[12:13] op_sel:[0,1,0]
	v_pk_fma_f32 v[14:15], v[42:43], v[146:147], v[14:15] op_sel_hi:[1,0,1]
	v_pk_fma_f32 v[16:17], v[44:45], v[146:147], v[16:17] op_sel_hi:[1,0,1]
	v_pk_fma_f32 v[6:7], v[42:43], v[146:147], v[6:7] op_sel:[0,1,0]
	v_pk_fma_f32 v[8:9], v[44:45], v[146:147], v[8:9] op_sel:[0,1,0]
	v_pk_fma_f32 v[18:19], v[42:43], v[148:149], v[18:19] op_sel_hi:[1,0,1]
	v_pk_fma_f32 v[20:21], v[44:45], v[148:149], v[20:21] op_sel_hi:[1,0,1]
	v_pk_fma_f32 v[26:27], v[42:43], v[148:149], v[26:27] op_sel:[0,1,0]
	v_pk_fma_f32 v[28:29], v[44:45], v[148:149], v[28:29] op_sel:[0,1,0]
	v_pk_fma_f32 v[30:31], v[42:43], v[150:151], v[30:31] op_sel_hi:[1,0,1]
	v_pk_fma_f32 v[32:33], v[44:45], v[150:151], v[32:33] op_sel_hi:[1,0,1]
	v_pk_fma_f32 v[22:23], v[42:43], v[150:151], v[22:23] op_sel:[0,1,0]
	v_pk_fma_f32 v[24:25], v[44:45], v[150:151], v[24:25] op_sel:[0,1,0]
	global_load_dwordx4 v[42:45], v[74:75], off
	v_lshl_add_u64 v[74:75], v[74:75], 0, s[36:37]
	s_waitcnt lgkmcnt(0)
	ds_read_b128 v[144:147], v78 offset:128
	ds_read_b128 v[148:151], v78 offset:144
	s_waitcnt vmcnt(31)
	v_pk_fma_f32 v[2:3], v[46:47], v[152:153], v[2:3] op_sel_hi:[1,0,1]
	v_pk_fma_f32 v[4:5], v[48:49], v[152:153], v[4:5] op_sel_hi:[1,0,1]
	v_pk_fma_f32 v[10:11], v[46:47], v[152:153], v[10:11] op_sel:[0,1,0]
	v_pk_fma_f32 v[12:13], v[48:49], v[152:153], v[12:13] op_sel:[0,1,0]
	v_pk_fma_f32 v[14:15], v[46:47], v[154:155], v[14:15] op_sel_hi:[1,0,1]
	v_pk_fma_f32 v[16:17], v[48:49], v[154:155], v[16:17] op_sel_hi:[1,0,1]
	v_pk_fma_f32 v[6:7], v[46:47], v[154:155], v[6:7] op_sel:[0,1,0]
	v_pk_fma_f32 v[8:9], v[48:49], v[154:155], v[8:9] op_sel:[0,1,0]
	v_pk_fma_f32 v[18:19], v[46:47], v[156:157], v[18:19] op_sel_hi:[1,0,1]
	v_pk_fma_f32 v[20:21], v[48:49], v[156:157], v[20:21] op_sel_hi:[1,0,1]
	v_pk_fma_f32 v[26:27], v[46:47], v[156:157], v[26:27] op_sel:[0,1,0]
	v_pk_fma_f32 v[28:29], v[48:49], v[156:157], v[28:29] op_sel:[0,1,0]
	v_pk_fma_f32 v[30:31], v[46:47], v[158:159], v[30:31] op_sel_hi:[1,0,1]
	v_pk_fma_f32 v[32:33], v[48:49], v[158:159], v[32:33] op_sel_hi:[1,0,1]
	v_pk_fma_f32 v[22:23], v[46:47], v[158:159], v[22:23] op_sel:[0,1,0]
	v_pk_fma_f32 v[24:25], v[48:49], v[158:159], v[24:25] op_sel:[0,1,0]
	global_load_dwordx4 v[46:49], v[74:75], off
	v_lshl_add_u64 v[74:75], v[74:75], 0, s[36:37]
	s_waitcnt lgkmcnt(0)
	ds_read_b128 v[152:155], v78 offset:160
	ds_read_b128 v[156:159], v78 offset:176
	s_waitcnt vmcnt(31)
	v_pk_fma_f32 v[2:3], v[50:51], v[144:145], v[2:3] op_sel_hi:[1,0,1]
	v_pk_fma_f32 v[4:5], v[52:53], v[144:145], v[4:5] op_sel_hi:[1,0,1]
	v_pk_fma_f32 v[10:11], v[50:51], v[144:145], v[10:11] op_sel:[0,1,0]
	v_pk_fma_f32 v[12:13], v[52:53], v[144:145], v[12:13] op_sel:[0,1,0]
	v_pk_fma_f32 v[14:15], v[50:51], v[146:147], v[14:15] op_sel_hi:[1,0,1]
	v_pk_fma_f32 v[16:17], v[52:53], v[146:147], v[16:17] op_sel_hi:[1,0,1]
	v_pk_fma_f32 v[6:7], v[50:51], v[146:147], v[6:7] op_sel:[0,1,0]
	v_pk_fma_f32 v[8:9], v[52:53], v[146:147], v[8:9] op_sel:[0,1,0]
	v_pk_fma_f32 v[18:19], v[50:51], v[148:149], v[18:19] op_sel_hi:[1,0,1]
	v_pk_fma_f32 v[20:21], v[52:53], v[148:149], v[20:21] op_sel_hi:[1,0,1]
	v_pk_fma_f32 v[26:27], v[50:51], v[148:149], v[26:27] op_sel:[0,1,0]
	v_pk_fma_f32 v[28:29], v[52:53], v[148:149], v[28:29] op_sel:[0,1,0]
	v_pk_fma_f32 v[30:31], v[50:51], v[150:151], v[30:31] op_sel_hi:[1,0,1]
	v_pk_fma_f32 v[32:33], v[52:53], v[150:151], v[32:33] op_sel_hi:[1,0,1]
	v_pk_fma_f32 v[22:23], v[50:51], v[150:151], v[22:23] op_sel:[0,1,0]
	v_pk_fma_f32 v[24:25], v[52:53], v[150:151], v[24:25] op_sel:[0,1,0]
	global_load_dwordx4 v[50:53], v[74:75], off
	v_lshl_add_u64 v[74:75], v[74:75], 0, s[36:37]
	s_waitcnt lgkmcnt(0)
	ds_read_b128 v[144:147], v78 offset:192
	ds_read_b128 v[148:151], v78 offset:208
	s_waitcnt vmcnt(31)
	v_pk_fma_f32 v[2:3], v[54:55], v[152:153], v[2:3] op_sel_hi:[1,0,1]
	v_pk_fma_f32 v[4:5], v[56:57], v[152:153], v[4:5] op_sel_hi:[1,0,1]
	v_pk_fma_f32 v[10:11], v[54:55], v[152:153], v[10:11] op_sel:[0,1,0]
	v_pk_fma_f32 v[12:13], v[56:57], v[152:153], v[12:13] op_sel:[0,1,0]
	v_pk_fma_f32 v[14:15], v[54:55], v[154:155], v[14:15] op_sel_hi:[1,0,1]
	v_pk_fma_f32 v[16:17], v[56:57], v[154:155], v[16:17] op_sel_hi:[1,0,1]
	v_pk_fma_f32 v[6:7], v[54:55], v[154:155], v[6:7] op_sel:[0,1,0]
	v_pk_fma_f32 v[8:9], v[56:57], v[154:155], v[8:9] op_sel:[0,1,0]
	v_pk_fma_f32 v[18:19], v[54:55], v[156:157], v[18:19] op_sel_hi:[1,0,1]
	v_pk_fma_f32 v[20:21], v[56:57], v[156:157], v[20:21] op_sel_hi:[1,0,1]
	v_pk_fma_f32 v[26:27], v[54:55], v[156:157], v[26:27] op_sel:[0,1,0]
	v_pk_fma_f32 v[28:29], v[56:57], v[156:157], v[28:29] op_sel:[0,1,0]
	v_pk_fma_f32 v[30:31], v[54:55], v[158:159], v[30:31] op_sel_hi:[1,0,1]
	v_pk_fma_f32 v[32:33], v[56:57], v[158:159], v[32:33] op_sel_hi:[1,0,1]
	v_pk_fma_f32 v[22:23], v[54:55], v[158:159], v[22:23] op_sel:[0,1,0]
	v_pk_fma_f32 v[24:25], v[56:57], v[158:159], v[24:25] op_sel:[0,1,0]
	global_load_dwordx4 v[54:57], v[74:75], off
	v_lshl_add_u64 v[74:75], v[74:75], 0, s[36:37]
	s_waitcnt lgkmcnt(0)
	ds_read_b128 v[152:155], v78 offset:224
	ds_read_b128 v[156:159], v78 offset:240
	s_waitcnt vmcnt(31)
; #define LAS __attribute__((address_space(3)))
; __device__ __forceinline__ void mod_item(int item, const float* w_ada, const float* b_ada, float* mod, LAS unsigned char* lds, int tid) {
;     ...
;     const float* wp = w_ada + ((size_t)layer * 2048 + ks * 64) * 6144 + col0 + quad * 4;
;     f32x4 a0 = {0, 0, 0, 0}, a1 = a0, a2 = a0, a3 = a0, a4 = a0, a5 = a0, a6 = a0, a7 = a0;
; #pragma unroll 8
;     for (int kk = 0; kk < 64; ++kk) {
;         const f32x4 w = *(const f32x4*)(wp + (size_t)kk * 6144);
;         const f32x4 c0 = *(const LAS f32x4*)(cond + (ks * 64 + kk) * 8), c1 = *(const LAS f32x4*)(cond + (ks * 64 + kk) * 8 + 4);
;         a0 += c0[0] * w; a1 += c0[1] * w; a2 += c0[2] * w; a3 += c0[3] * w; a4 += c1[0] * w; a5 += c1[1] * w; a6 += c1[2] * w; a7 += c1[3] * w;
;     }
	v_pk_fma_f32 v[2:3], v[58:59], v[144:145], v[2:3] op_sel_hi:[1,0,1]
	v_pk_fma_f32 v[4:5], v[60:61], v[144:145], v[4:5] op_sel_hi:[1,0,1]
	v_pk_fma_f32 v[10:11], v[58:59], v[144:145], v[10:11] op_sel:[0,1,0]
	v_pk_fma_f32 v[12:13], v[60:61], v[144:145], v[12:13] op_sel:[0,1,0]
	v_pk_fma_f32 v[14:15], v[58:59], v[146:147], v[14:15] op_sel_hi:[1,0,1]
	v_pk_fma_f32 v[16:17], v[60:61], v[146:147], v[16:17] op_sel_hi:[1,0,1]
	v_pk_fma_f32 v[6:7], v[58:59], v[146:147], v[6:7] op_sel:[0,1,0]
	v_pk_fma_f32 v[8:9], v[60:61], v[146:147], v[8:9] op_sel:[0,1,0]
	v_pk_fma_f32 v[18:19], v[58:59], v[148:149], v[18:19] op_sel_hi:[1,0,1]
	v_pk_fma_f32 v[20:21], v[60:61], v[148:149], v[20:21] op_sel_hi:[1,0,1]
	v_pk_fma_f32 v[26:27], v[58:59], v[148:149], v[26:27] op_sel:[0,1,0]
	v_pk_fma_f32 v[28:29], v[60:61], v[148:149], v[28:29] op_sel:[0,1,0]
	v_pk_fma_f32 v[30:31], v[58:59], v[150:151], v[30:31] op_sel_hi:[1,0,1]
	v_pk_fma_f32 v[32:33], v[60:61], v[150:151], v[32:33] op_sel_hi:[1,0,1]
	v_pk_fma_f32 v[22:23], v[58:59], v[150:151], v[22:23] op_sel:[0,1,0]
	v_pk_fma_f32 v[24:25], v[60:61], v[150:151], v[24:25] op_sel:[0,1,0]
	global_load_dwordx4 v[58:61], v[74:75], off
	v_lshl_add_u64 v[74:75], v[74:75], 0, s[36:37]
	s_waitcnt lgkmcnt(0)
	ds_read_b128 v[144:147], v78 offset:256
	ds_read_b128 v[148:151], v78 offset:272
	s_waitcnt vmcnt(31)
	v_pk_fma_f32 v[2:3], v[62:63], v[152:153], v[2:3] op_sel_hi:[1,0,1]
	v_pk_fma_f32 v[4:5], v[64:65], v[152:153], v[4:5] op_sel_hi:[1,0,1]
	v_pk_fma_f32 v[10:11], v[62:63], v[152:153], v[10:11] op_sel:[0,1,0]
	v_pk_fma_f32 v[12:13], v[64:65], v[152:153], v[12:13] op_sel:[0,1,0]
	v_pk_fma_f32 v[14:15], v[62:63], v[154:155], v[14:15] op_sel_hi:[1,0,1]
	v_pk_fma_f32 v[16:17], v[64:65], v[154:155], v[16:17] op_sel_hi:[1,0,1]
	v_pk_fma_f32 v[6:7], v[62:63], v[154:155], v[6:7] op_sel:[0,1,0]
	v_pk_fma_f32 v[8:9], v[64:65], v[154:155], v[8:9] op_sel:[0,1,0]
	v_pk_fma_f32 v[18:19], v[62:63], v[156:157], v[18:19] op_sel_hi:[1,0,1]
	v_pk_fma_f32 v[20:21], v[64:65], v[156:157], v[20:21] op_sel_hi:[1,0,1]
	v_pk_fma_f32 v[26:27], v[62:63], v[156:157], v[26:27] op_sel:[0,1,0]
	v_pk_fma_f32 v[28:29], v[64:65], v[156:157], v[28:29] op_sel:[0,1,0]
	v_pk_fma_f32 v[30:31], v[62:63], v[158:159], v[30:31] op_sel_hi:[1,0,1]
	v_pk_fma_f32 v[32:33], v[64:65], v[158:159], v[32:33] op_sel_hi:[1,0,1]
	v_pk_fma_f32 v[22:23], v[62:63], v[158:159], v[22:23] op_sel:[0,1,0]
	v_pk_fma_f32 v[24:25], v[64:65], v[158:159], v[24:25] op_sel:[0,1,0]
	global_load_dwordx4 v[62:65], v[74:75], off
	v_lshl_add_u64 v[74:75], v[74:75], 0, s[36:37]
	s_waitcnt lgkmcnt(0)
	ds_read_b128 v[152:155], v78 offset:288
	ds_read_b128 v[156:159], v78 offset:304
	s_waitcnt vmcnt(31)
	v_pk_fma_f32 v[2:3], v[80:81], v[144:145], v[2:3] op_sel_hi:[1,0,1]
	v_pk_fma_f32 v[4:5], v[82:83], v[144:145], v[4:5] op_sel_hi:[1,0,1]
	v_pk_fma_f32 v[10:11], v[80:81], v[144:145], v[10:11] op_sel:[0,1,0]
	v_pk_fma_f32 v[12:13], v[82:83], v[144:145], v[12:13] op_sel:[0,1,0]
	v_pk_fma_f32 v[14:15], v[80:81], v[146:147], v[14:15] op_sel_hi:[1,0,1]
	v_pk_fma_f32 v[16:17], v[82:83], v[146:147], v[16:17] op_sel_hi:[1,0,1]
	v_pk_fma_f32 v[6:7], v[80:81], v[146:147], v[6:7] op_sel:[0,1,0]
	v_pk_fma_f32 v[8:9], v[82:83], v[146:147], v[8:9] op_sel:[0,1,0]
	v_pk_fma_f32 v[18:19], v[80:81], v[148:149], v[18:19] op_sel_hi:[1,0,1]
	v_pk_fma_f32 v[20:21], v[82:83], v[148:149], v[20:21] op_sel_hi:[1,0,1]
	v_pk_fma_f32 v[26:27], v[80:81], v[148:149], v[26:27] op_sel:[0,1,0]
	v_pk_fma_f32 v[28:29], v[82:83], v[148:149], v[28:29] op_sel:[0,1,0]
	v_pk_fma_f32 v[30:31], v[80:81], v[150:151], v[30:31] op_sel_hi:[1,0,1]
	v_pk_fma_f32 v[32:33], v[82:83], v[150:151], v[32:33] op_sel_hi:[1,0,1]
	v_pk_fma_f32 v[22:23], v[80:81], v[150:151], v[22:23] op_sel:[0,1,0]
	v_pk_fma_f32 v[24:25], v[82:83], v[150:151], v[24:25] op_sel:[0,1,0]
	global_load_dwordx4 v[80:83], v[74:75], off
	v_lshl_add_u64 v[74:75], v[74:75], 0, s[36:37]
	s_waitcnt lgkmcnt(0)
	ds_read_b128 v[144:147], v78 offset:320
	ds_read_b128 v[148:151], v78 offset:336
	s_waitcnt vmcnt(31)
	v_pk_fma_f32 v[2:3], v[84:85], v[152:153], v[2:3] op_sel_hi:[1,0,1]
	v_pk_fma_f32 v[4:5], v[86:87], v[152:153], v[4:5] op_sel_hi:[1,0,1]
	v_pk_fma_f32 v[10:11], v[84:85], v[152:153], v[10:11] op_sel:[0,1,0]
	v_pk_fma_f32 v[12:13], v[86:87], v[152:153], v[12:13] op_sel:[0,1,0]
	v_pk_fma_f32 v[14:15], v[84:85], v[154:155], v[14:15] op_sel_hi:[1,0,1]
	v_pk_fma_f32 v[16:17], v[86:87], v[154:155], v[16:17] op_sel_hi:[1,0,1]
	v_pk_fma_f32 v[6:7], v[84:85], v[154:155], v[6:7] op_sel:[0,1,0]
	v_pk_fma_f32 v[8:9], v[86:87], v[154:155], v[8:9] op_sel:[0,1,0]
	v_pk_fma_f32 v[18:19], v[84:85], v[156:157], v[18:19] op_sel_hi:[1,0,1]
	v_pk_fma_f32 v[20:21], v[86:87], v[156:157], v[20:21] op_sel_hi:[1,0,1]
	v_pk_fma_f32 v[26:27], v[84:85], v[156:157], v[26:27] op_sel:[0,1,0]
	v_pk_fma_f32 v[28:29], v[86:87], v[156:157], v[28:29] op_sel:[0,1,0]
	v_pk_fma_f32 v[30:31], v[84:85], v[158:159], v[30:31] op_sel_hi:[1,0,1]
	v_pk_fma_f32 v[32:33], v[86:87], v[158:159], v[32:33] op_sel_hi:[1,0,1]
	v_pk_fma_f32 v[22:23], v[84:85], v[158:159], v[22:23] op_sel:[0,1,0]
	v_pk_fma_f32 v[24:25], v[86:87], v[158:159], v[24:25] op_sel:[0,1,0]
	global_load_dwordx4 v[84:87], v[74:75], off
	v_lshl_add_u64 v[74:75], v[74:75], 0, s[36:37]
	s_waitcnt lgkmcnt(0)
	ds_read_b128 v[152:155], v78 offset:352
	ds_read_b128 v[156:159], v78 offset:368
	s_waitcnt vmcnt(31)
; #define LAS __attribute__((address_space(3)))
; __device__ __forceinline__ void mod_item(int item, const float* w_ada, const float* b_ada, float* mod, LAS unsigned char* lds, int tid) {
;     ...
;     const float* wp = w_ada + ((size_t)layer * 2048 + ks * 64) * 6144 + col0 + quad * 4;
;     f32x4 a0 = {0, 0, 0, 0}, a1 = a0, a2 = a0, a3 = a0, a4 = a0, a5 = a0, a6 = a0, a7 = a0;
; #pragma unroll 8
;     for (int kk = 0; kk < 64; ++kk) {
;         const f32x4 w = *(const f32x4*)(wp + (size_t)kk * 6144);
;         const f32x4 c0 = *(const LAS f32x4*)(cond + (ks * 64 + kk) * 8), c1 = *(const LAS f32x4*)(cond + (ks * 64 + kk) * 8 + 4);
;         a0 += c0[0] * w; a1 += c0[1] * w; a2 += c0[2] * w; a3 += c0[3] * w; a4 += c1[0] * w; a5 += c1[1] * w; a6 += c1[2] * w; a7 += c1[3] * w;
;     }
	v_pk_fma_f32 v[2:3], v[88:89], v[144:145], v[2:3] op_sel_hi:[1,0,1]
	v_pk_fma_f32 v[4:5], v[90:91], v[144:145], v[4:5] op_sel_hi:[1,0,1]
	v_pk_fma_f32 v[10:11], v[88:89], v[144:145], v[10:11] op_sel:[0,1,0]
	v_pk_fma_f32 v[12:13], v[90:91], v[144:145], v[12:13] op_sel:[0,1,0]
	v_pk_fma_f32 v[14:15], v[88:89], v[146:147], v[14:15] op_sel_hi:[1,0,1]
	v_pk_fma_f32 v[16:17], v[90:91], v[146:147], v[16:17] op_sel_hi:[1,0,1]
	v_pk_fma_f32 v[6:7], v[88:89], v[146:147], v[6:7] op_sel:[0,1,0]
	v_pk_fma_f32 v[8:9], v[90:91], v[146:147], v[8:9] op_sel:[0,1,0]
	v_pk_fma_f32 v[18:19], v[88:89], v[148:149], v[18:19] op_sel_hi:[1,0,1]
	v_pk_fma_f32 v[20:21], v[90:91], v[148:149], v[20:21] op_sel_hi:[1,0,1]
	v_pk_fma_f32 v[26:27], v[88:89], v[148:149], v[26:27] op_sel:[0,1,0]
	v_pk_fma_f32 v[28:29], v[90:91], v[148:149], v[28:29] op_sel:[0,1,0]
	v_pk_fma_f32 v[30:31], v[88:89], v[150:151], v[30:31] op_sel_hi:[1,0,1]
	v_pk_fma_f32 v[32:33], v[90:91], v[150:151], v[32:33] op_sel_hi:[1,0,1]
	v_pk_fma_f32 v[22:23], v[88:89], v[150:151], v[22:23] op_sel:[0,1,0]
	v_pk_fma_f32 v[24:25], v[90:91], v[150:151], v[24:25] op_sel:[0,1,0]
	global_load_dwordx4 v[88:91], v[74:75], off
	v_lshl_add_u64 v[74:75], v[74:75], 0, s[36:37]
	s_waitcnt lgkmcnt(0)
	ds_read_b128 v[144:147], v78 offset:384
	ds_read_b128 v[148:151], v78 offset:400
	s_waitcnt vmcnt(31)
	v_pk_fma_f32 v[2:3], v[92:93], v[152:153], v[2:3] op_sel_hi:[1,0,1]
	v_pk_fma_f32 v[4:5], v[94:95], v[152:153], v[4:5] op_sel_hi:[1,0,1]
	v_pk_fma_f32 v[10:11], v[92:93], v[152:153], v[10:11] op_sel:[0,1,0]
	v_pk_fma_f32 v[12:13], v[94:95], v[152:153], v[12:13] op_sel:[0,1,0]
	v_pk_fma_f32 v[14:15], v[92:93], v[154:155], v[14:15] op_sel_hi:[1,0,1]
	v_pk_fma_f32 v[16:17], v[94:95], v[154:155], v[16:17] op_sel_hi:[1,0,1]
	v_pk_fma_f32 v[6:7], v[92:93], v[154:155], v[6:7] op_sel:[0,1,0]
	v_pk_fma_f32 v[8:9], v[94:95], v[154:155], v[8:9] op_sel:[0,1,0]
	v_pk_fma_f32 v[18:19], v[92:93], v[156:157], v[18:19] op_sel_hi:[1,0,1]
	v_pk_fma_f32 v[20:21], v[94:95], v[156:157], v[20:21] op_sel_hi:[1,0,1]
	v_pk_fma_f32 v[26:27], v[92:93], v[156:157], v[26:27] op_sel:[0,1,0]
	v_pk_fma_f32 v[28:29], v[94:95], v[156:157], v[28:29] op_sel:[0,1,0]
	v_pk_fma_f32 v[30:31], v[92:93], v[158:159], v[30:31] op_sel_hi:[1,0,1]
	v_pk_fma_f32 v[32:33], v[94:95], v[158:159], v[32:33] op_sel_hi:[1,0,1]
	v_pk_fma_f32 v[22:23], v[92:93], v[158:159], v[22:23] op_sel:[0,1,0]
	v_pk_fma_f32 v[24:25], v[94:95], v[158:159], v[24:25] op_sel:[0,1,0]
	global_load_dwordx4 v[92:95], v[74:75], off
	v_lshl_add_u64 v[74:75], v[74:75], 0, s[36:37]
	s_waitcnt lgkmcnt(0)
	ds_read_b128 v[152:155], v78 offset:416
	ds_read_b128 v[156:159], v78 offset:432
	s_waitcnt vmcnt(31)
	v_pk_fma_f32 v[2:3], v[96:97], v[144:145], v[2:3] op_sel_hi:[1,0,1]
	v_pk_fma_f32 v[4:5], v[98:99], v[144:145], v[4:5] op_sel_hi:[1,0,1]
	v_pk_fma_f32 v[10:11], v[96:97], v[144:145], v[10:11] op_sel:[0,1,0]
	v_pk_fma_f32 v[12:13], v[98:99], v[144:145], v[12:13] op_sel:[0,1,0]
	v_pk_fma_f32 v[14:15], v[96:97], v[146:147], v[14:15] op_sel_hi:[1,0,1]
	v_pk_fma_f32 v[16:17], v[98:99], v[146:147], v[16:17] op_sel_hi:[1,0,1]
	v_pk_fma_f32 v[6:7], v[96:97], v[146:147], v[6:7] op_sel:[0,1,0]
	v_pk_fma_f32 v[8:9], v[98:99], v[146:147], v[8:9] op_sel:[0,1,0]
	v_pk_fma_f32 v[18:19], v[96:97], v[148:149], v[18:19] op_sel_hi:[1,0,1]
	v_pk_fma_f32 v[20:21], v[98:99], v[148:149], v[20:21] op_sel_hi:[1,0,1]
	v_pk_fma_f32 v[26:27], v[96:97], v[148:149], v[26:27] op_sel:[0,1,0]
	v_pk_fma_f32 v[28:29], v[98:99], v[148:149], v[28:29] op_sel:[0,1,0]
	v_pk_fma_f32 v[30:31], v[96:97], v[150:151], v[30:31] op_sel_hi:[1,0,1]
	v_pk_fma_f32 v[32:33], v[98:99], v[150:151], v[32:33] op_sel_hi:[1,0,1]
	v_pk_fma_f32 v[22:23], v[96:97], v[150:151], v[22:23] op_sel:[0,1,0]
	v_pk_fma_f32 v[24:25], v[98:99], v[150:151], v[24:25] op_sel:[0,1,0]
	global_load_dwordx4 v[96:99], v[74:75], off
	v_lshl_add_u64 v[74:75], v[74:75], 0, s[36:37]
	s_waitcnt lgkmcnt(0)
	ds_read_b128 v[144:147], v78 offset:448
	ds_read_b128 v[148:151], v78 offset:464
	s_waitcnt vmcnt(31)
	v_pk_fma_f32 v[2:3], v[100:101], v[152:153], v[2:3] op_sel_hi:[1,0,1]
	v_pk_fma_f32 v[4:5], v[102:103], v[152:153], v[4:5] op_sel_hi:[1,0,1]
	v_pk_fma_f32 v[10:11], v[100:101], v[152:153], v[10:11] op_sel:[0,1,0]
	v_pk_fma_f32 v[12:13], v[102:103], v[152:153], v[12:13] op_sel:[0,1,0]
	v_pk_fma_f32 v[14:15], v[100:101], v[154:155], v[14:15] op_sel_hi:[1,0,1]
	v_pk_fma_f32 v[16:17], v[102:103], v[154:155], v[16:17] op_sel_hi:[1,0,1]
	v_pk_fma_f32 v[6:7], v[100:101], v[154:155], v[6:7] op_sel:[0,1,0]
	v_pk_fma_f32 v[8:9], v[102:103], v[154:155], v[8:9] op_sel:[0,1,0]
	v_pk_fma_f32 v[18:19], v[100:101], v[156:157], v[18:19] op_sel_hi:[1,0,1]
	v_pk_fma_f32 v[20:21], v[102:103], v[156:157], v[20:21] op_sel_hi:[1,0,1]
	v_pk_fma_f32 v[26:27], v[100:101], v[156:157], v[26:27] op_sel:[0,1,0]
	v_pk_fma_f32 v[28:29], v[102:103], v[156:157], v[28:29] op_sel:[0,1,0]
	v_pk_fma_f32 v[30:31], v[100:101], v[158:159], v[30:31] op_sel_hi:[1,0,1]
	v_pk_fma_f32 v[32:33], v[102:103], v[158:159], v[32:33] op_sel_hi:[1,0,1]
	v_pk_fma_f32 v[22:23], v[100:101], v[158:159], v[22:23] op_sel:[0,1,0]
	v_pk_fma_f32 v[24:25], v[102:103], v[158:159], v[24:25] op_sel:[0,1,0]
	global_load_dwordx4 v[100:103], v[74:75], off
	v_lshl_add_u64 v[74:75], v[74:75], 0, s[36:37]
	s_waitcnt lgkmcnt(0)
	ds_read_b128 v[152:155], v78 offset:480
	ds_read_b128 v[156:159], v78 offset:496
	s_waitcnt vmcnt(31)
; #define LAS __attribute__((address_space(3)))
; __device__ __forceinline__ void mod_item(int item, const float* w_ada, const float* b_ada, float* mod, LAS unsigned char* lds, int tid) {
;     ...
;     const float* wp = w_ada + ((size_t)layer * 2048 + ks * 64) * 6144 + col0 + quad * 4;
;     f32x4 a0 = {0, 0, 0, 0}, a1 = a0, a2 = a0, a3 = a0, a4 = a0, a5 = a0, a6 = a0, a7 = a0;
; #pragma unroll 8
;     for (int kk = 0; kk < 64; ++kk) {
;         const f32x4 w = *(const f32x4*)(wp + (size_t)kk * 6144);
;         const f32x4 c0 = *(const LAS f32x4*)(cond + (ks * 64 + kk) * 8), c1 = *(const LAS f32x4*)(cond + (ks * 64 + kk) * 8 + 4);
;         a0 += c0[0] * w; a1 += c0[1] * w; a2 += c0[2] * w; a3 += c0[3] * w; a4 += c1[0] * w; a5 += c1[1] * w; a6 += c1[2] * w; a7 += c1[3] * w;
;     }
	v_pk_fma_f32 v[2:3], v[104:105], v[144:145], v[2:3] op_sel_hi:[1,0,1]
	v_pk_fma_f32 v[4:5], v[106:107], v[144:145], v[4:5] op_sel_hi:[1,0,1]
	v_pk_fma_f32 v[10:11], v[104:105], v[144:145], v[10:11] op_sel:[0,1,0]
	v_pk_fma_f32 v[12:13], v[106:107], v[144:145], v[12:13] op_sel:[0,1,0]
	v_pk_fma_f32 v[14:15], v[104:105], v[146:147], v[14:15] op_sel_hi:[1,0,1]
	v_pk_fma_f32 v[16:17], v[106:107], v[146:147], v[16:17] op_sel_hi:[1,0,1]
	v_pk_fma_f32 v[6:7], v[104:105], v[146:147], v[6:7] op_sel:[0,1,0]
	v_pk_fma_f32 v[8:9], v[106:107], v[146:147], v[8:9] op_sel:[0,1,0]
	v_pk_fma_f32 v[18:19], v[104:105], v[148:149], v[18:19] op_sel_hi:[1,0,1]
	v_pk_fma_f32 v[20:21], v[106:107], v[148:149], v[20:21] op_sel_hi:[1,0,1]
	v_pk_fma_f32 v[26:27], v[104:105], v[148:149], v[26:27] op_sel:[0,1,0]
	v_pk_fma_f32 v[28:29], v[106:107], v[148:149], v[28:29] op_sel:[0,1,0]
	v_pk_fma_f32 v[30:31], v[104:105], v[150:151], v[30:31] op_sel_hi:[1,0,1]
	v_pk_fma_f32 v[32:33], v[106:107], v[150:151], v[32:33] op_sel_hi:[1,0,1]
	v_pk_fma_f32 v[22:23], v[104:105], v[150:151], v[22:23] op_sel:[0,1,0]
	v_pk_fma_f32 v[24:25], v[106:107], v[150:151], v[24:25] op_sel:[0,1,0]
	global_load_dwordx4 v[104:107], v[74:75], off
	v_lshl_add_u64 v[74:75], v[74:75], 0, s[36:37]
	s_waitcnt lgkmcnt(0)
	ds_read_b128 v[144:147], v78 offset:512
	ds_read_b128 v[148:151], v78 offset:528
	s_waitcnt vmcnt(31)
	v_pk_fma_f32 v[2:3], v[108:109], v[152:153], v[2:3] op_sel_hi:[1,0,1]
	v_pk_fma_f32 v[4:5], v[110:111], v[152:153], v[4:5] op_sel_hi:[1,0,1]
	v_pk_fma_f32 v[10:11], v[108:109], v[152:153], v[10:11] op_sel:[0,1,0]
	v_pk_fma_f32 v[12:13], v[110:111], v[152:153], v[12:13] op_sel:[0,1,0]
	v_pk_fma_f32 v[14:15], v[108:109], v[154:155], v[14:15] op_sel_hi:[1,0,1]
	v_pk_fma_f32 v[16:17], v[110:111], v[154:155], v[16:17] op_sel_hi:[1,0,1]
	v_pk_fma_f32 v[6:7], v[108:109], v[154:155], v[6:7] op_sel:[0,1,0]
	v_pk_fma_f32 v[8:9], v[110:111], v[154:155], v[8:9] op_sel:[0,1,0]
	v_pk_fma_f32 v[18:19], v[108:109], v[156:157], v[18:19] op_sel_hi:[1,0,1]
	v_pk_fma_f32 v[20:21], v[110:111], v[156:157], v[20:21] op_sel_hi:[1,0,1]
	v_pk_fma_f32 v[26:27], v[108:109], v[156:157], v[26:27] op_sel:[0,1,0]
	v_pk_fma_f32 v[28:29], v[110:111], v[156:157], v[28:29] op_sel:[0,1,0]
	v_pk_fma_f32 v[30:31], v[108:109], v[158:159], v[30:31] op_sel_hi:[1,0,1]
	v_pk_fma_f32 v[32:33], v[110:111], v[158:159], v[32:33] op_sel_hi:[1,0,1]
	v_pk_fma_f32 v[22:23], v[108:109], v[158:159], v[22:23] op_sel:[0,1,0]
	v_pk_fma_f32 v[24:25], v[110:111], v[158:159], v[24:25] op_sel:[0,1,0]
	global_load_dwordx4 v[108:111], v[74:75], off
	v_lshl_add_u64 v[74:75], v[74:75], 0, s[36:37]
	s_waitcnt lgkmcnt(0)
	ds_read_b128 v[152:155], v78 offset:544
	ds_read_b128 v[156:159], v78 offset:560
	s_waitcnt vmcnt(31)
	v_pk_fma_f32 v[2:3], v[112:113], v[144:145], v[2:3] op_sel_hi:[1,0,1]
	v_pk_fma_f32 v[4:5], v[114:115], v[144:145], v[4:5] op_sel_hi:[1,0,1]
	v_pk_fma_f32 v[10:11], v[112:113], v[144:145], v[10:11] op_sel:[0,1,0]
	v_pk_fma_f32 v[12:13], v[114:115], v[144:145], v[12:13] op_sel:[0,1,0]
	v_pk_fma_f32 v[14:15], v[112:113], v[146:147], v[14:15] op_sel_hi:[1,0,1]
	v_pk_fma_f32 v[16:17], v[114:115], v[146:147], v[16:17] op_sel_hi:[1,0,1]
	v_pk_fma_f32 v[6:7], v[112:113], v[146:147], v[6:7] op_sel:[0,1,0]
	v_pk_fma_f32 v[8:9], v[114:115], v[146:147], v[8:9] op_sel:[0,1,0]
	v_pk_fma_f32 v[18:19], v[112:113], v[148:149], v[18:19] op_sel_hi:[1,0,1]
	v_pk_fma_f32 v[20:21], v[114:115], v[148:149], v[20:21] op_sel_hi:[1,0,1]
	v_pk_fma_f32 v[26:27], v[112:113], v[148:149], v[26:27] op_sel:[0,1,0]
	v_pk_fma_f32 v[28:29], v[114:115], v[148:149], v[28:29] op_sel:[0,1,0]
	v_pk_fma_f32 v[30:31], v[112:113], v[150:151], v[30:31] op_sel_hi:[1,0,1]
	v_pk_fma_f32 v[32:33], v[114:115], v[150:151], v[32:33] op_sel_hi:[1,0,1]
	v_pk_fma_f32 v[22:23], v[112:113], v[150:151], v[22:23] op_sel:[0,1,0]
	v_pk_fma_f32 v[24:25], v[114:115], v[150:151], v[24:25] op_sel:[0,1,0]
	global_load_dwordx4 v[112:115], v[74:75], off
	v_lshl_add_u64 v[74:75], v[74:75], 0, s[36:37]
	s_waitcnt lgkmcnt(0)
	ds_read_b128 v[144:147], v78 offset:576
	ds_read_b128 v[148:151], v78 offset:592
	s_waitcnt vmcnt(31)
	v_pk_fma_f32 v[2:3], v[116:117], v[152:153], v[2:3] op_sel_hi:[1,0,1]
	v_pk_fma_f32 v[4:5], v[118:119], v[152:153], v[4:5] op_sel_hi:[1,0,1]
	v_pk_fma_f32 v[10:11], v[116:117], v[152:153], v[10:11] op_sel:[0,1,0]
	v_pk_fma_f32 v[12:13], v[118:119], v[152:153], v[12:13] op_sel:[0,1,0]
	v_pk_fma_f32 v[14:15], v[116:117], v[154:155], v[14:15] op_sel_hi:[1,0,1]
	v_pk_fma_f32 v[16:17], v[118:119], v[154:155], v[16:17] op_sel_hi:[1,0,1]
	v_pk_fma_f32 v[6:7], v[116:117], v[154:155], v[6:7] op_sel:[0,1,0]
	v_pk_fma_f32 v[8:9], v[118:119], v[154:155], v[8:9] op_sel:[0,1,0]
	v_pk_fma_f32 v[18:19], v[116:117], v[156:157], v[18:19] op_sel_hi:[1,0,1]
	v_pk_fma_f32 v[20:21], v[118:119], v[156:157], v[20:21] op_sel_hi:[1,0,1]
	v_pk_fma_f32 v[26:27], v[116:117], v[156:157], v[26:27] op_sel:[0,1,0]
	v_pk_fma_f32 v[28:29], v[118:119], v[156:157], v[28:29] op_sel:[0,1,0]
	v_pk_fma_f32 v[30:31], v[116:117], v[158:159], v[30:31] op_sel_hi:[1,0,1]
	v_pk_fma_f32 v[32:33], v[118:119], v[158:159], v[32:33] op_sel_hi:[1,0,1]
	v_pk_fma_f32 v[22:23], v[116:117], v[158:159], v[22:23] op_sel:[0,1,0]
	v_pk_fma_f32 v[24:25], v[118:119], v[158:159], v[24:25] op_sel:[0,1,0]
	global_load_dwordx4 v[116:119], v[74:75], off
	v_lshl_add_u64 v[74:75], v[74:75], 0, s[36:37]
	s_waitcnt lgkmcnt(0)
	ds_read_b128 v[152:155], v78 offset:608
	ds_read_b128 v[156:159], v78 offset:624
	s_waitcnt vmcnt(31)
; #define LAS __attribute__((address_space(3)))
; __device__ __forceinline__ void mod_item(int item, const float* w_ada, const float* b_ada, float* mod, LAS unsigned char* lds, int tid) {
;     ...
;     const float* wp = w_ada + ((size_t)layer * 2048 + ks * 64) * 6144 + col0 + quad * 4;
;     f32x4 a0 = {0, 0, 0, 0}, a1 = a0, a2 = a0, a3 = a0, a4 = a0, a5 = a0, a6 = a0, a7 = a0;
; #pragma unroll 8
;     for (int kk = 0; kk < 64; ++kk) {
;         const f32x4 w = *(const f32x4*)(wp + (size_t)kk * 6144);
;         const f32x4 c0 = *(const LAS f32x4*)(cond + (ks * 64 + kk) * 8), c1 = *(const LAS f32x4*)(cond + (ks * 64 + kk) * 8 + 4);
;         a0 += c0[0] * w; a1 += c0[1] * w; a2 += c0[2] * w; a3 += c0[3] * w; a4 += c1[0] * w; a5 += c1[1] * w; a6 += c1[2] * w; a7 += c1[3] * w;
;     }
	v_pk_fma_f32 v[2:3], v[120:121], v[144:145], v[2:3] op_sel_hi:[1,0,1]
	v_pk_fma_f32 v[4:5], v[122:123], v[144:145], v[4:5] op_sel_hi:[1,0,1]
	v_pk_fma_f32 v[10:11], v[120:121], v[144:145], v[10:11] op_sel:[0,1,0]
	v_pk_fma_f32 v[12:13], v[122:123], v[144:145], v[12:13] op_sel:[0,1,0]
	v_pk_fma_f32 v[14:15], v[120:121], v[146:147], v[14:15] op_sel_hi:[1,0,1]
	v_pk_fma_f32 v[16:17], v[122:123], v[146:147], v[16:17] op_sel_hi:[1,0,1]
	v_pk_fma_f32 v[6:7], v[120:121], v[146:147], v[6:7] op_sel:[0,1,0]
	v_pk_fma_f32 v[8:9], v[122:123], v[146:147], v[8:9] op_sel:[0,1,0]
	v_pk_fma_f32 v[18:19], v[120:121], v[148:149], v[18:19] op_sel_hi:[1,0,1]
	v_pk_fma_f32 v[20:21], v[122:123], v[148:149], v[20:21] op_sel_hi:[1,0,1]
	v_pk_fma_f32 v[26:27], v[120:121], v[148:149], v[26:27] op_sel:[0,1,0]
	v_pk_fma_f32 v[28:29], v[122:123], v[148:149], v[28:29] op_sel:[0,1,0]
	v_pk_fma_f32 v[30:31], v[120:121], v[150:151], v[30:31] op_sel_hi:[1,0,1]
	v_pk_fma_f32 v[32:33], v[122:123], v[150:151], v[32:33] op_sel_hi:[1,0,1]
	v_pk_fma_f32 v[22:23], v[120:121], v[150:151], v[22:23] op_sel:[0,1,0]
	v_pk_fma_f32 v[24:25], v[122:123], v[150:151], v[24:25] op_sel:[0,1,0]
	global_load_dwordx4 v[120:123], v[74:75], off
	v_lshl_add_u64 v[74:75], v[74:75], 0, s[36:37]
	s_waitcnt lgkmcnt(0)
	ds_read_b128 v[144:147], v78 offset:640
	ds_read_b128 v[148:151], v78 offset:656
	s_waitcnt vmcnt(31)
	v_pk_fma_f32 v[2:3], v[124:125], v[152:153], v[2:3] op_sel_hi:[1,0,1]
	v_pk_fma_f32 v[4:5], v[126:127], v[152:153], v[4:5] op_sel_hi:[1,0,1]
	v_pk_fma_f32 v[10:11], v[124:125], v[152:153], v[10:11] op_sel:[0,1,0]
	v_pk_fma_f32 v[12:13], v[126:127], v[152:153], v[12:13] op_sel:[0,1,0]
	v_pk_fma_f32 v[14:15], v[124:125], v[154:155], v[14:15] op_sel_hi:[1,0,1]
	v_pk_fma_f32 v[16:17], v[126:127], v[154:155], v[16:17] op_sel_hi:[1,0,1]
	v_pk_fma_f32 v[6:7], v[124:125], v[154:155], v[6:7] op_sel:[0,1,0]
	v_pk_fma_f32 v[8:9], v[126:127], v[154:155], v[8:9] op_sel:[0,1,0]
	v_pk_fma_f32 v[18:19], v[124:125], v[156:157], v[18:19] op_sel_hi:[1,0,1]
	v_pk_fma_f32 v[20:21], v[126:127], v[156:157], v[20:21] op_sel_hi:[1,0,1]
	v_pk_fma_f32 v[26:27], v[124:125], v[156:157], v[26:27] op_sel:[0,1,0]
	v_pk_fma_f32 v[28:29], v[126:127], v[156:157], v[28:29] op_sel:[0,1,0]
	v_pk_fma_f32 v[30:31], v[124:125], v[158:159], v[30:31] op_sel_hi:[1,0,1]
	v_pk_fma_f32 v[32:33], v[126:127], v[158:159], v[32:33] op_sel_hi:[1,0,1]
	v_pk_fma_f32 v[22:23], v[124:125], v[158:159], v[22:23] op_sel:[0,1,0]
	v_pk_fma_f32 v[24:25], v[126:127], v[158:159], v[24:25] op_sel:[0,1,0]
	global_load_dwordx4 v[124:127], v[74:75], off
	v_lshl_add_u64 v[74:75], v[74:75], 0, s[36:37]
	s_waitcnt lgkmcnt(0)
	ds_read_b128 v[152:155], v78 offset:672
	ds_read_b128 v[156:159], v78 offset:688
	s_waitcnt vmcnt(31)
	v_pk_fma_f32 v[2:3], v[128:129], v[144:145], v[2:3] op_sel_hi:[1,0,1]
	v_pk_fma_f32 v[4:5], v[130:131], v[144:145], v[4:5] op_sel_hi:[1,0,1]
	v_pk_fma_f32 v[10:11], v[128:129], v[144:145], v[10:11] op_sel:[0,1,0]
	v_pk_fma_f32 v[12:13], v[130:131], v[144:145], v[12:13] op_sel:[0,1,0]
	v_pk_fma_f32 v[14:15], v[128:129], v[146:147], v[14:15] op_sel_hi:[1,0,1]
	v_pk_fma_f32 v[16:17], v[130:131], v[146:147], v[16:17] op_sel_hi:[1,0,1]
	v_pk_fma_f32 v[6:7], v[128:129], v[146:147], v[6:7] op_sel:[0,1,0]
	v_pk_fma_f32 v[8:9], v[130:131], v[146:147], v[8:9] op_sel:[0,1,0]
	v_pk_fma_f32 v[18:19], v[128:129], v[148:149], v[18:19] op_sel_hi:[1,0,1]
	v_pk_fma_f32 v[20:21], v[130:131], v[148:149], v[20:21] op_sel_hi:[1,0,1]
	v_pk_fma_f32 v[26:27], v[128:129], v[148:149], v[26:27] op_sel:[0,1,0]
	v_pk_fma_f32 v[28:29], v[130:131], v[148:149], v[28:29] op_sel:[0,1,0]
	v_pk_fma_f32 v[30:31], v[128:129], v[150:151], v[30:31] op_sel_hi:[1,0,1]
	v_pk_fma_f32 v[32:33], v[130:131], v[150:151], v[32:33] op_sel_hi:[1,0,1]
	v_pk_fma_f32 v[22:23], v[128:129], v[150:151], v[22:23] op_sel:[0,1,0]
	v_pk_fma_f32 v[24:25], v[130:131], v[150:151], v[24:25] op_sel:[0,1,0]
	global_load_dwordx4 v[128:131], v[74:75], off
	v_lshl_add_u64 v[74:75], v[74:75], 0, s[36:37]
	s_waitcnt lgkmcnt(0)
	ds_read_b128 v[144:147], v78 offset:704
	ds_read_b128 v[148:151], v78 offset:720
	s_waitcnt vmcnt(31)
	v_pk_fma_f32 v[2:3], v[132:133], v[152:153], v[2:3] op_sel_hi:[1,0,1]
	v_pk_fma_f32 v[4:5], v[134:135], v[152:153], v[4:5] op_sel_hi:[1,0,1]
	v_pk_fma_f32 v[10:11], v[132:133], v[152:153], v[10:11] op_sel:[0,1,0]
	v_pk_fma_f32 v[12:13], v[134:135], v[152:153], v[12:13] op_sel:[0,1,0]
	v_pk_fma_f32 v[14:15], v[132:133], v[154:155], v[14:15] op_sel_hi:[1,0,1]
	v_pk_fma_f32 v[16:17], v[134:135], v[154:155], v[16:17] op_sel_hi:[1,0,1]
	v_pk_fma_f32 v[6:7], v[132:133], v[154:155], v[6:7] op_sel:[0,1,0]
	v_pk_fma_f32 v[8:9], v[134:135], v[154:155], v[8:9] op_sel:[0,1,0]
	v_pk_fma_f32 v[18:19], v[132:133], v[156:157], v[18:19] op_sel_hi:[1,0,1]
	v_pk_fma_f32 v[20:21], v[134:135], v[156:157], v[20:21] op_sel_hi:[1,0,1]
	v_pk_fma_f32 v[26:27], v[132:133], v[156:157], v[26:27] op_sel:[0,1,0]
	v_pk_fma_f32 v[28:29], v[134:135], v[156:157], v[28:29] op_sel:[0,1,0]
	v_pk_fma_f32 v[30:31], v[132:133], v[158:159], v[30:31] op_sel_hi:[1,0,1]
	v_pk_fma_f32 v[32:33], v[134:135], v[158:159], v[32:33] op_sel_hi:[1,0,1]
	v_pk_fma_f32 v[22:23], v[132:133], v[158:159], v[22:23] op_sel:[0,1,0]
	v_pk_fma_f32 v[24:25], v[134:135], v[158:159], v[24:25] op_sel:[0,1,0]
	global_load_dwordx4 v[132:135], v[74:75], off
	v_lshl_add_u64 v[74:75], v[74:75], 0, s[36:37]
	s_waitcnt lgkmcnt(0)
	ds_read_b128 v[152:155], v78 offset:736
	ds_read_b128 v[156:159], v78 offset:752
	s_waitcnt vmcnt(31)
; #define LAS __attribute__((address_space(3)))
; __device__ __forceinline__ void mod_item(int item, const float* w_ada, const float* b_ada, float* mod, LAS unsigned char* lds, int tid) {
;     ...
;     const float* wp = w_ada + ((size_t)layer * 2048 + ks * 64) * 6144 + col0 + quad * 4;
;     f32x4 a0 = {0, 0, 0, 0}, a1 = a0, a2 = a0, a3 = a0, a4 = a0, a5 = a0, a6 = a0, a7 = a0;
; #pragma unroll 8
;     for (int kk = 0; kk < 64; ++kk) {
;         const f32x4 w = *(const f32x4*)(wp + (size_t)kk * 6144);
;         const f32x4 c0 = *(const LAS f32x4*)(cond + (ks * 64 + kk) * 8), c1 = *(const LAS f32x4*)(cond + (ks * 64 + kk) * 8 + 4);
;         a0 += c0[0] * w; a1 += c0[1] * w; a2 += c0[2] * w; a3 += c0[3] * w; a4 += c1[0] * w; a5 += c1[1] * w; a6 += c1[2] * w; a7 += c1[3] * w;
;     }
	v_pk_fma_f32 v[2:3], v[136:137], v[144:145], v[2:3] op_sel_hi:[1,0,1]
	v_pk_fma_f32 v[4:5], v[138:139], v[144:145], v[4:5] op_sel_hi:[1,0,1]
	v_pk_fma_f32 v[10:11], v[136:137], v[144:145], v[10:11] op_sel:[0,1,0]
	v_pk_fma_f32 v[12:13], v[138:139], v[144:145], v[12:13] op_sel:[0,1,0]
	v_pk_fma_f32 v[14:15], v[136:137], v[146:147], v[14:15] op_sel_hi:[1,0,1]
	v_pk_fma_f32 v[16:17], v[138:139], v[146:147], v[16:17] op_sel_hi:[1,0,1]
	v_pk_fma_f32 v[6:7], v[136:137], v[146:147], v[6:7] op_sel:[0,1,0]
	v_pk_fma_f32 v[8:9], v[138:139], v[146:147], v[8:9] op_sel:[0,1,0]
	v_pk_fma_f32 v[18:19], v[136:137], v[148:149], v[18:19] op_sel_hi:[1,0,1]
	v_pk_fma_f32 v[20:21], v[138:139], v[148:149], v[20:21] op_sel_hi:[1,0,1]
	v_pk_fma_f32 v[26:27], v[136:137], v[148:149], v[26:27] op_sel:[0,1,0]
	v_pk_fma_f32 v[28:29], v[138:139], v[148:149], v[28:29] op_sel:[0,1,0]
	v_pk_fma_f32 v[30:31], v[136:137], v[150:151], v[30:31] op_sel_hi:[1,0,1]
	v_pk_fma_f32 v[32:33], v[138:139], v[150:151], v[32:33] op_sel_hi:[1,0,1]
	v_pk_fma_f32 v[22:23], v[136:137], v[150:151], v[22:23] op_sel:[0,1,0]
	v_pk_fma_f32 v[24:25], v[138:139], v[150:151], v[24:25] op_sel:[0,1,0]
	global_load_dwordx4 v[136:139], v[74:75], off
	v_lshl_add_u64 v[74:75], v[74:75], 0, s[36:37]
	s_waitcnt lgkmcnt(0)
	ds_read_b128 v[144:147], v78 offset:768
	ds_read_b128 v[148:151], v78 offset:784
	s_waitcnt vmcnt(31)
	v_pk_fma_f32 v[2:3], v[140:141], v[152:153], v[2:3] op_sel_hi:[1,0,1]
	v_pk_fma_f32 v[4:5], v[142:143], v[152:153], v[4:5] op_sel_hi:[1,0,1]
	v_pk_fma_f32 v[10:11], v[140:141], v[152:153], v[10:11] op_sel:[0,1,0]
	v_pk_fma_f32 v[12:13], v[142:143], v[152:153], v[12:13] op_sel:[0,1,0]
	v_pk_fma_f32 v[14:15], v[140:141], v[154:155], v[14:15] op_sel_hi:[1,0,1]
	v_pk_fma_f32 v[16:17], v[142:143], v[154:155], v[16:17] op_sel_hi:[1,0,1]
	v_pk_fma_f32 v[6:7], v[140:141], v[154:155], v[6:7] op_sel:[0,1,0]
	v_pk_fma_f32 v[8:9], v[142:143], v[154:155], v[8:9] op_sel:[0,1,0]
	v_pk_fma_f32 v[18:19], v[140:141], v[156:157], v[18:19] op_sel_hi:[1,0,1]
	v_pk_fma_f32 v[20:21], v[142:143], v[156:157], v[20:21] op_sel_hi:[1,0,1]
	v_pk_fma_f32 v[26:27], v[140:141], v[156:157], v[26:27] op_sel:[0,1,0]
	v_pk_fma_f32 v[28:29], v[142:143], v[156:157], v[28:29] op_sel:[0,1,0]
	v_pk_fma_f32 v[30:31], v[140:141], v[158:159], v[30:31] op_sel_hi:[1,0,1]
	v_pk_fma_f32 v[32:33], v[142:143], v[158:159], v[32:33] op_sel_hi:[1,0,1]
	v_pk_fma_f32 v[22:23], v[140:141], v[158:159], v[22:23] op_sel:[0,1,0]
	v_pk_fma_f32 v[24:25], v[142:143], v[158:159], v[24:25] op_sel:[0,1,0]
	global_load_dwordx4 v[140:143], v[74:75], off
	v_lshl_add_u64 v[74:75], v[74:75], 0, s[36:37]
	s_waitcnt lgkmcnt(0)
	ds_read_b128 v[152:155], v78 offset:800
	ds_read_b128 v[156:159], v78 offset:816
	s_waitcnt vmcnt(31)
	v_pk_fma_f32 v[2:3], v[176:177], v[144:145], v[2:3] op_sel_hi:[1,0,1]
	v_pk_fma_f32 v[4:5], v[178:179], v[144:145], v[4:5] op_sel_hi:[1,0,1]
	v_pk_fma_f32 v[10:11], v[176:177], v[144:145], v[10:11] op_sel:[0,1,0]
	v_pk_fma_f32 v[12:13], v[178:179], v[144:145], v[12:13] op_sel:[0,1,0]
	v_pk_fma_f32 v[14:15], v[176:177], v[146:147], v[14:15] op_sel_hi:[1,0,1]
	v_pk_fma_f32 v[16:17], v[178:179], v[146:147], v[16:17] op_sel_hi:[1,0,1]
	v_pk_fma_f32 v[6:7], v[176:177], v[146:147], v[6:7] op_sel:[0,1,0]
	v_pk_fma_f32 v[8:9], v[178:179], v[146:147], v[8:9] op_sel:[0,1,0]
	v_pk_fma_f32 v[18:19], v[176:177], v[148:149], v[18:19] op_sel_hi:[1,0,1]
	v_pk_fma_f32 v[20:21], v[178:179], v[148:149], v[20:21] op_sel_hi:[1,0,1]
	v_pk_fma_f32 v[26:27], v[176:177], v[148:149], v[26:27] op_sel:[0,1,0]
	v_pk_fma_f32 v[28:29], v[178:179], v[148:149], v[28:29] op_sel:[0,1,0]
	v_pk_fma_f32 v[30:31], v[176:177], v[150:151], v[30:31] op_sel_hi:[1,0,1]
	v_pk_fma_f32 v[32:33], v[178:179], v[150:151], v[32:33] op_sel_hi:[1,0,1]
	v_pk_fma_f32 v[22:23], v[176:177], v[150:151], v[22:23] op_sel:[0,1,0]
	v_pk_fma_f32 v[24:25], v[178:179], v[150:151], v[24:25] op_sel:[0,1,0]
	global_load_dwordx4 v[176:179], v[74:75], off
	v_lshl_add_u64 v[74:75], v[74:75], 0, s[36:37]
	s_waitcnt lgkmcnt(0)
	ds_read_b128 v[144:147], v78 offset:832
	ds_read_b128 v[148:151], v78 offset:848
	s_waitcnt vmcnt(31)
	v_pk_fma_f32 v[2:3], v[180:181], v[152:153], v[2:3] op_sel_hi:[1,0,1]
	v_pk_fma_f32 v[4:5], v[182:183], v[152:153], v[4:5] op_sel_hi:[1,0,1]
	v_pk_fma_f32 v[10:11], v[180:181], v[152:153], v[10:11] op_sel:[0,1,0]
	v_pk_fma_f32 v[12:13], v[182:183], v[152:153], v[12:13] op_sel:[0,1,0]
	v_pk_fma_f32 v[14:15], v[180:181], v[154:155], v[14:15] op_sel_hi:[1,0,1]
	v_pk_fma_f32 v[16:17], v[182:183], v[154:155], v[16:17] op_sel_hi:[1,0,1]
	v_pk_fma_f32 v[6:7], v[180:181], v[154:155], v[6:7] op_sel:[0,1,0]
	v_pk_fma_f32 v[8:9], v[182:183], v[154:155], v[8:9] op_sel:[0,1,0]
	v_pk_fma_f32 v[18:19], v[180:181], v[156:157], v[18:19] op_sel_hi:[1,0,1]
	v_pk_fma_f32 v[20:21], v[182:183], v[156:157], v[20:21] op_sel_hi:[1,0,1]
	v_pk_fma_f32 v[26:27], v[180:181], v[156:157], v[26:27] op_sel:[0,1,0]
	v_pk_fma_f32 v[28:29], v[182:183], v[156:157], v[28:29] op_sel:[0,1,0]
	v_pk_fma_f32 v[30:31], v[180:181], v[158:159], v[30:31] op_sel_hi:[1,0,1]
	v_pk_fma_f32 v[32:33], v[182:183], v[158:159], v[32:33] op_sel_hi:[1,0,1]
	v_pk_fma_f32 v[22:23], v[180:181], v[158:159], v[22:23] op_sel:[0,1,0]
	v_pk_fma_f32 v[24:25], v[182:183], v[158:159], v[24:25] op_sel:[0,1,0]
	global_load_dwordx4 v[180:183], v[74:75], off
	v_lshl_add_u64 v[74:75], v[74:75], 0, s[36:37]
	s_waitcnt lgkmcnt(0)
	ds_read_b128 v[152:155], v78 offset:864
	ds_read_b128 v[156:159], v78 offset:880
	s_waitcnt vmcnt(31)
; #define LAS __attribute__((address_space(3)))
; __device__ __forceinline__ void mod_item(int item, const float* w_ada, const float* b_ada, float* mod, LAS unsigned char* lds, int tid) {
;     ...
;     const float* wp = w_ada + ((size_t)layer * 2048 + ks * 64) * 6144 + col0 + quad * 4;
;     f32x4 a0 = {0, 0, 0, 0}, a1 = a0, a2 = a0, a3 = a0, a4 = a0, a5 = a0, a6 = a0, a7 = a0;
; #pragma unroll 8
;     for (int kk = 0; kk < 64; ++kk) {
;         const f32x4 w = *(const f32x4*)(wp + (size_t)kk * 6144);
;         const f32x4 c0 = *(const LAS f32x4*)(cond + (ks * 64 + kk) * 8), c1 = *(const LAS f32x4*)(cond + (ks * 64 + kk) * 8 + 4);
;         a0 += c0[0] * w; a1 += c0[1] * w; a2 += c0[2] * w; a3 += c0[3] * w; a4 += c1[0] * w; a5 += c1[1] * w; a6 += c1[2] * w; a7 += c1[3] * w;
;     }
	v_pk_fma_f32 v[2:3], v[184:185], v[144:145], v[2:3] op_sel_hi:[1,0,1]
	v_pk_fma_f32 v[4:5], v[186:187], v[144:145], v[4:5] op_sel_hi:[1,0,1]
	v_pk_fma_f32 v[10:11], v[184:185], v[144:145], v[10:11] op_sel:[0,1,0]
	v_pk_fma_f32 v[12:13], v[186:187], v[144:145], v[12:13] op_sel:[0,1,0]
	v_pk_fma_f32 v[14:15], v[184:185], v[146:147], v[14:15] op_sel_hi:[1,0,1]
	v_pk_fma_f32 v[16:17], v[186:187], v[146:147], v[16:17] op_sel_hi:[1,0,1]
	v_pk_fma_f32 v[6:7], v[184:185], v[146:147], v[6:7] op_sel:[0,1,0]
	v_pk_fma_f32 v[8:9], v[186:187], v[146:147], v[8:9] op_sel:[0,1,0]
	v_pk_fma_f32 v[18:19], v[184:185], v[148:149], v[18:19] op_sel_hi:[1,0,1]
	v_pk_fma_f32 v[20:21], v[186:187], v[148:149], v[20:21] op_sel_hi:[1,0,1]
	v_pk_fma_f32 v[26:27], v[184:185], v[148:149], v[26:27] op_sel:[0,1,0]
	v_pk_fma_f32 v[28:29], v[186:187], v[148:149], v[28:29] op_sel:[0,1,0]
	v_pk_fma_f32 v[30:31], v[184:185], v[150:151], v[30:31] op_sel_hi:[1,0,1]
	v_pk_fma_f32 v[32:33], v[186:187], v[150:151], v[32:33] op_sel_hi:[1,0,1]
	v_pk_fma_f32 v[22:23], v[184:185], v[150:151], v[22:23] op_sel:[0,1,0]
	v_pk_fma_f32 v[24:25], v[186:187], v[150:151], v[24:25] op_sel:[0,1,0]
	global_load_dwordx4 v[184:187], v[74:75], off
	v_lshl_add_u64 v[74:75], v[74:75], 0, s[36:37]
	s_waitcnt lgkmcnt(0)
	ds_read_b128 v[144:147], v78 offset:896
	ds_read_b128 v[148:151], v78 offset:912
	s_waitcnt vmcnt(31)
	v_pk_fma_f32 v[2:3], v[188:189], v[152:153], v[2:3] op_sel_hi:[1,0,1]
	v_pk_fma_f32 v[4:5], v[190:191], v[152:153], v[4:5] op_sel_hi:[1,0,1]
	v_pk_fma_f32 v[10:11], v[188:189], v[152:153], v[10:11] op_sel:[0,1,0]
	v_pk_fma_f32 v[12:13], v[190:191], v[152:153], v[12:13] op_sel:[0,1,0]
	v_pk_fma_f32 v[14:15], v[188:189], v[154:155], v[14:15] op_sel_hi:[1,0,1]
	v_pk_fma_f32 v[16:17], v[190:191], v[154:155], v[16:17] op_sel_hi:[1,0,1]
	v_pk_fma_f32 v[6:7], v[188:189], v[154:155], v[6:7] op_sel:[0,1,0]
	v_pk_fma_f32 v[8:9], v[190:191], v[154:155], v[8:9] op_sel:[0,1,0]
	v_pk_fma_f32 v[18:19], v[188:189], v[156:157], v[18:19] op_sel_hi:[1,0,1]
	v_pk_fma_f32 v[20:21], v[190:191], v[156:157], v[20:21] op_sel_hi:[1,0,1]
	v_pk_fma_f32 v[26:27], v[188:189], v[156:157], v[26:27] op_sel:[0,1,0]
	v_pk_fma_f32 v[28:29], v[190:191], v[156:157], v[28:29] op_sel:[0,1,0]
	v_pk_fma_f32 v[30:31], v[188:189], v[158:159], v[30:31] op_sel_hi:[1,0,1]
	v_pk_fma_f32 v[32:33], v[190:191], v[158:159], v[32:33] op_sel_hi:[1,0,1]
	v_pk_fma_f32 v[22:23], v[188:189], v[158:159], v[22:23] op_sel:[0,1,0]
	v_pk_fma_f32 v[24:25], v[190:191], v[158:159], v[24:25] op_sel:[0,1,0]
	global_load_dwordx4 v[188:191], v[74:75], off
	v_lshl_add_u64 v[74:75], v[74:75], 0, s[36:37]
	s_waitcnt lgkmcnt(0)
	ds_read_b128 v[152:155], v78 offset:928
	ds_read_b128 v[156:159], v78 offset:944
	s_waitcnt vmcnt(31)
	v_pk_fma_f32 v[2:3], v[192:193], v[144:145], v[2:3] op_sel_hi:[1,0,1]
	v_pk_fma_f32 v[4:5], v[194:195], v[144:145], v[4:5] op_sel_hi:[1,0,1]
	v_pk_fma_f32 v[10:11], v[192:193], v[144:145], v[10:11] op_sel:[0,1,0]
	v_pk_fma_f32 v[12:13], v[194:195], v[144:145], v[12:13] op_sel:[0,1,0]
	v_pk_fma_f32 v[14:15], v[192:193], v[146:147], v[14:15] op_sel_hi:[1,0,1]
	v_pk_fma_f32 v[16:17], v[194:195], v[146:147], v[16:17] op_sel_hi:[1,0,1]
	v_pk_fma_f32 v[6:7], v[192:193], v[146:147], v[6:7] op_sel:[0,1,0]
	v_pk_fma_f32 v[8:9], v[194:195], v[146:147], v[8:9] op_sel:[0,1,0]
	v_pk_fma_f32 v[18:19], v[192:193], v[148:149], v[18:19] op_sel_hi:[1,0,1]
	v_pk_fma_f32 v[20:21], v[194:195], v[148:149], v[20:21] op_sel_hi:[1,0,1]
	v_pk_fma_f32 v[26:27], v[192:193], v[148:149], v[26:27] op_sel:[0,1,0]
	v_pk_fma_f32 v[28:29], v[194:195], v[148:149], v[28:29] op_sel:[0,1,0]
	v_pk_fma_f32 v[30:31], v[192:193], v[150:151], v[30:31] op_sel_hi:[1,0,1]
	v_pk_fma_f32 v[32:33], v[194:195], v[150:151], v[32:33] op_sel_hi:[1,0,1]
	v_pk_fma_f32 v[22:23], v[192:193], v[150:151], v[22:23] op_sel:[0,1,0]
	v_pk_fma_f32 v[24:25], v[194:195], v[150:151], v[24:25] op_sel:[0,1,0]
	global_load_dwordx4 v[192:195], v[74:75], off
	v_lshl_add_u64 v[74:75], v[74:75], 0, s[36:37]
	s_waitcnt lgkmcnt(0)
	ds_read_b128 v[144:147], v78 offset:960
	ds_read_b128 v[148:151], v78 offset:976
	s_waitcnt vmcnt(31)
	v_pk_fma_f32 v[2:3], v[196:197], v[152:153], v[2:3] op_sel_hi:[1,0,1]
	v_pk_fma_f32 v[4:5], v[198:199], v[152:153], v[4:5] op_sel_hi:[1,0,1]
	v_pk_fma_f32 v[10:11], v[196:197], v[152:153], v[10:11] op_sel:[0,1,0]
	v_pk_fma_f32 v[12:13], v[198:199], v[152:153], v[12:13] op_sel:[0,1,0]
	v_pk_fma_f32 v[14:15], v[196:197], v[154:155], v[14:15] op_sel_hi:[1,0,1]
	v_pk_fma_f32 v[16:17], v[198:199], v[154:155], v[16:17] op_sel_hi:[1,0,1]
	v_pk_fma_f32 v[6:7], v[196:197], v[154:155], v[6:7] op_sel:[0,1,0]
	v_pk_fma_f32 v[8:9], v[198:199], v[154:155], v[8:9] op_sel:[0,1,0]
	v_pk_fma_f32 v[18:19], v[196:197], v[156:157], v[18:19] op_sel_hi:[1,0,1]
	v_pk_fma_f32 v[20:21], v[198:199], v[156:157], v[20:21] op_sel_hi:[1,0,1]
	v_pk_fma_f32 v[26:27], v[196:197], v[156:157], v[26:27] op_sel:[0,1,0]
	v_pk_fma_f32 v[28:29], v[198:199], v[156:157], v[28:29] op_sel:[0,1,0]
	v_pk_fma_f32 v[30:31], v[196:197], v[158:159], v[30:31] op_sel_hi:[1,0,1]
	v_pk_fma_f32 v[32:33], v[198:199], v[158:159], v[32:33] op_sel_hi:[1,0,1]
	v_pk_fma_f32 v[22:23], v[196:197], v[158:159], v[22:23] op_sel:[0,1,0]
	v_pk_fma_f32 v[24:25], v[198:199], v[158:159], v[24:25] op_sel:[0,1,0]
	global_load_dwordx4 v[196:199], v[74:75], off
	v_lshl_add_u64 v[74:75], v[74:75], 0, s[36:37]
	s_waitcnt lgkmcnt(0)
	ds_read_b128 v[152:155], v78 offset:992
	ds_read_b128 v[156:159], v78 offset:1008
	s_waitcnt vmcnt(31)
; #define LAS __attribute__((address_space(3)))
; __device__ __forceinline__ void mod_item(int item, const float* w_ada, const float* b_ada, float* mod, LAS unsigned char* lds, int tid) {
;     ...
;     const float* wp = w_ada + ((size_t)layer * 2048 + ks * 64) * 6144 + col0 + quad * 4;
;     f32x4 a0 = {0, 0, 0, 0}, a1 = a0, a2 = a0, a3 = a0, a4 = a0, a5 = a0, a6 = a0, a7 = a0;
; #pragma unroll 8
;     for (int kk = 0; kk < 64; ++kk) {
;         const f32x4 w = *(const f32x4*)(wp + (size_t)kk * 6144);
;         const f32x4 c0 = *(const LAS f32x4*)(cond + (ks * 64 + kk) * 8), c1 = *(const LAS f32x4*)(cond + (ks * 64 + kk) * 8 + 4);
;         a0 += c0[0] * w; a1 += c0[1] * w; a2 += c0[2] * w; a3 += c0[3] * w; a4 += c1[0] * w; a5 += c1[1] * w; a6 += c1[2] * w; a7 += c1[3] * w;
;     }
	v_pk_fma_f32 v[2:3], v[200:201], v[144:145], v[2:3] op_sel_hi:[1,0,1]
	v_pk_fma_f32 v[4:5], v[202:203], v[144:145], v[4:5] op_sel_hi:[1,0,1]
	v_pk_fma_f32 v[10:11], v[200:201], v[144:145], v[10:11] op_sel:[0,1,0]
	v_pk_fma_f32 v[12:13], v[202:203], v[144:145], v[12:13] op_sel:[0,1,0]
	v_pk_fma_f32 v[14:15], v[200:201], v[146:147], v[14:15] op_sel_hi:[1,0,1]
	v_pk_fma_f32 v[16:17], v[202:203], v[146:147], v[16:17] op_sel_hi:[1,0,1]
	v_pk_fma_f32 v[6:7], v[200:201], v[146:147], v[6:7] op_sel:[0,1,0]
	v_pk_fma_f32 v[8:9], v[202:203], v[146:147], v[8:9] op_sel:[0,1,0]
	v_pk_fma_f32 v[18:19], v[200:201], v[148:149], v[18:19] op_sel_hi:[1,0,1]
	v_pk_fma_f32 v[20:21], v[202:203], v[148:149], v[20:21] op_sel_hi:[1,0,1]
	v_pk_fma_f32 v[26:27], v[200:201], v[148:149], v[26:27] op_sel:[0,1,0]
	v_pk_fma_f32 v[28:29], v[202:203], v[148:149], v[28:29] op_sel:[0,1,0]
	v_pk_fma_f32 v[30:31], v[200:201], v[150:151], v[30:31] op_sel_hi:[1,0,1]
	v_pk_fma_f32 v[32:33], v[202:203], v[150:151], v[32:33] op_sel_hi:[1,0,1]
	v_pk_fma_f32 v[22:23], v[200:201], v[150:151], v[22:23] op_sel:[0,1,0]
	v_pk_fma_f32 v[24:25], v[202:203], v[150:151], v[24:25] op_sel:[0,1,0]
	global_load_dwordx4 v[200:203], v[74:75], off
	v_lshl_add_u64 v[74:75], v[74:75], 0, s[36:37]
	s_waitcnt lgkmcnt(0)
	ds_read_b128 v[144:147], v78 offset:1024
	ds_read_b128 v[148:151], v78 offset:1040
	s_waitcnt vmcnt(31)
	v_pk_fma_f32 v[2:3], v[204:205], v[152:153], v[2:3] op_sel_hi:[1,0,1]
	v_pk_fma_f32 v[4:5], v[206:207], v[152:153], v[4:5] op_sel_hi:[1,0,1]
	v_pk_fma_f32 v[10:11], v[204:205], v[152:153], v[10:11] op_sel:[0,1,0]
	v_pk_fma_f32 v[12:13], v[206:207], v[152:153], v[12:13] op_sel:[0,1,0]
	v_pk_fma_f32 v[14:15], v[204:205], v[154:155], v[14:15] op_sel_hi:[1,0,1]
	v_pk_fma_f32 v[16:17], v[206:207], v[154:155], v[16:17] op_sel_hi:[1,0,1]
	v_pk_fma_f32 v[6:7], v[204:205], v[154:155], v[6:7] op_sel:[0,1,0]
	v_pk_fma_f32 v[8:9], v[206:207], v[154:155], v[8:9] op_sel:[0,1,0]
	v_pk_fma_f32 v[18:19], v[204:205], v[156:157], v[18:19] op_sel_hi:[1,0,1]
	v_pk_fma_f32 v[20:21], v[206:207], v[156:157], v[20:21] op_sel_hi:[1,0,1]
	v_pk_fma_f32 v[26:27], v[204:205], v[156:157], v[26:27] op_sel:[0,1,0]
	v_pk_fma_f32 v[28:29], v[206:207], v[156:157], v[28:29] op_sel:[0,1,0]
	v_pk_fma_f32 v[30:31], v[204:205], v[158:159], v[30:31] op_sel_hi:[1,0,1]
	v_pk_fma_f32 v[32:33], v[206:207], v[158:159], v[32:33] op_sel_hi:[1,0,1]
	v_pk_fma_f32 v[22:23], v[204:205], v[158:159], v[22:23] op_sel:[0,1,0]
	v_pk_fma_f32 v[24:25], v[206:207], v[158:159], v[24:25] op_sel:[0,1,0]
	global_load_dwordx4 v[204:207], v[74:75], off
	v_lshl_add_u64 v[74:75], v[74:75], 0, s[36:37]
	s_waitcnt lgkmcnt(0)
	ds_read_b128 v[152:155], v78 offset:1056
	ds_read_b128 v[156:159], v78 offset:1072
	s_waitcnt vmcnt(31)
	v_pk_fma_f32 v[2:3], v[34:35], v[144:145], v[2:3] op_sel_hi:[1,0,1]
	v_pk_fma_f32 v[4:5], v[36:37], v[144:145], v[4:5] op_sel_hi:[1,0,1]
	v_pk_fma_f32 v[10:11], v[34:35], v[144:145], v[10:11] op_sel:[0,1,0]
	v_pk_fma_f32 v[12:13], v[36:37], v[144:145], v[12:13] op_sel:[0,1,0]
	v_pk_fma_f32 v[14:15], v[34:35], v[146:147], v[14:15] op_sel_hi:[1,0,1]
	v_pk_fma_f32 v[16:17], v[36:37], v[146:147], v[16:17] op_sel_hi:[1,0,1]
	v_pk_fma_f32 v[6:7], v[34:35], v[146:147], v[6:7] op_sel:[0,1,0]
	v_pk_fma_f32 v[8:9], v[36:37], v[146:147], v[8:9] op_sel:[0,1,0]
	v_pk_fma_f32 v[18:19], v[34:35], v[148:149], v[18:19] op_sel_hi:[1,0,1]
	v_pk_fma_f32 v[20:21], v[36:37], v[148:149], v[20:21] op_sel_hi:[1,0,1]
	v_pk_fma_f32 v[26:27], v[34:35], v[148:149], v[26:27] op_sel:[0,1,0]
	v_pk_fma_f32 v[28:29], v[36:37], v[148:149], v[28:29] op_sel:[0,1,0]
	v_pk_fma_f32 v[30:31], v[34:35], v[150:151], v[30:31] op_sel_hi:[1,0,1]
	v_pk_fma_f32 v[32:33], v[36:37], v[150:151], v[32:33] op_sel_hi:[1,0,1]
	v_pk_fma_f32 v[22:23], v[34:35], v[150:151], v[22:23] op_sel:[0,1,0]
	v_pk_fma_f32 v[24:25], v[36:37], v[150:151], v[24:25] op_sel:[0,1,0]
	s_waitcnt lgkmcnt(0)
	ds_read_b128 v[144:147], v78 offset:1088
	ds_read_b128 v[148:151], v78 offset:1104
	s_waitcnt vmcnt(30)
	v_pk_fma_f32 v[2:3], v[38:39], v[152:153], v[2:3] op_sel_hi:[1,0,1]
	v_pk_fma_f32 v[4:5], v[40:41], v[152:153], v[4:5] op_sel_hi:[1,0,1]
	v_pk_fma_f32 v[10:11], v[38:39], v[152:153], v[10:11] op_sel:[0,1,0]
	v_pk_fma_f32 v[12:13], v[40:41], v[152:153], v[12:13] op_sel:[0,1,0]
	v_pk_fma_f32 v[14:15], v[38:39], v[154:155], v[14:15] op_sel_hi:[1,0,1]
	v_pk_fma_f32 v[16:17], v[40:41], v[154:155], v[16:17] op_sel_hi:[1,0,1]
	v_pk_fma_f32 v[6:7], v[38:39], v[154:155], v[6:7] op_sel:[0,1,0]
	v_pk_fma_f32 v[8:9], v[40:41], v[154:155], v[8:9] op_sel:[0,1,0]
	v_pk_fma_f32 v[18:19], v[38:39], v[156:157], v[18:19] op_sel_hi:[1,0,1]
	v_pk_fma_f32 v[20:21], v[40:41], v[156:157], v[20:21] op_sel_hi:[1,0,1]
	v_pk_fma_f32 v[26:27], v[38:39], v[156:157], v[26:27] op_sel:[0,1,0]
	v_pk_fma_f32 v[28:29], v[40:41], v[156:157], v[28:29] op_sel:[0,1,0]
	v_pk_fma_f32 v[30:31], v[38:39], v[158:159], v[30:31] op_sel_hi:[1,0,1]
	v_pk_fma_f32 v[32:33], v[40:41], v[158:159], v[32:33] op_sel_hi:[1,0,1]
	v_pk_fma_f32 v[22:23], v[38:39], v[158:159], v[22:23] op_sel:[0,1,0]
	v_pk_fma_f32 v[24:25], v[40:41], v[158:159], v[24:25] op_sel:[0,1,0]
	s_waitcnt lgkmcnt(0)
	ds_read_b128 v[152:155], v78 offset:1120
	ds_read_b128 v[156:159], v78 offset:1136
	s_waitcnt vmcnt(29)
; #define LAS __attribute__((address_space(3)))
; __device__ __forceinline__ void mod_item(int item, const float* w_ada, const float* b_ada, float* mod, LAS unsigned char* lds, int tid) {
;     ...
;     const float* wp = w_ada + ((size_t)layer * 2048 + ks * 64) * 6144 + col0 + quad * 4;
;     f32x4 a0 = {0, 0, 0, 0}, a1 = a0, a2 = a0, a3 = a0, a4 = a0, a5 = a0, a6 = a0, a7 = a0;
; #pragma unroll 8
;     for (int kk = 0; kk < 64; ++kk) {
;         const f32x4 w = *(const f32x4*)(wp + (size_t)kk * 6144);
;         const f32x4 c0 = *(const LAS f32x4*)(cond + (ks * 64 + kk) * 8), c1 = *(const LAS f32x4*)(cond + (ks * 64 + kk) * 8 + 4);
;         a0 += c0[0] * w; a1 += c0[1] * w; a2 += c0[2] * w; a3 += c0[3] * w; a4 += c1[0] * w; a5 += c1[1] * w; a6 += c1[2] * w; a7 += c1[3] * w;
;     }
	v_pk_fma_f32 v[2:3], v[42:43], v[144:145], v[2:3] op_sel_hi:[1,0,1]
	v_pk_fma_f32 v[4:5], v[44:45], v[144:145], v[4:5] op_sel_hi:[1,0,1]
	v_pk_fma_f32 v[10:11], v[42:43], v[144:145], v[10:11] op_sel:[0,1,0]
	v_pk_fma_f32 v[12:13], v[44:45], v[144:145], v[12:13] op_sel:[0,1,0]
	v_pk_fma_f32 v[14:15], v[42:43], v[146:147], v[14:15] op_sel_hi:[1,0,1]
	v_pk_fma_f32 v[16:17], v[44:45], v[146:147], v[16:17] op_sel_hi:[1,0,1]
	v_pk_fma_f32 v[6:7], v[42:43], v[146:147], v[6:7] op_sel:[0,1,0]
	v_pk_fma_f32 v[8:9], v[44:45], v[146:147], v[8:9] op_sel:[0,1,0]
	v_pk_fma_f32 v[18:19], v[42:43], v[148:149], v[18:19] op_sel_hi:[1,0,1]
	v_pk_fma_f32 v[20:21], v[44:45], v[148:149], v[20:21] op_sel_hi:[1,0,1]
	v_pk_fma_f32 v[26:27], v[42:43], v[148:149], v[26:27] op_sel:[0,1,0]
	v_pk_fma_f32 v[28:29], v[44:45], v[148:149], v[28:29] op_sel:[0,1,0]
	v_pk_fma_f32 v[30:31], v[42:43], v[150:151], v[30:31] op_sel_hi:[1,0,1]
	v_pk_fma_f32 v[32:33], v[44:45], v[150:151], v[32:33] op_sel_hi:[1,0,1]
	v_pk_fma_f32 v[22:23], v[42:43], v[150:151], v[22:23] op_sel:[0,1,0]
	v_pk_fma_f32 v[24:25], v[44:45], v[150:151], v[24:25] op_sel:[0,1,0]
	s_waitcnt lgkmcnt(0)
	ds_read_b128 v[144:147], v78 offset:1152
	ds_read_b128 v[148:151], v78 offset:1168
	s_waitcnt vmcnt(28)
	v_pk_fma_f32 v[2:3], v[46:47], v[152:153], v[2:3] op_sel_hi:[1,0,1]
	v_pk_fma_f32 v[4:5], v[48:49], v[152:153], v[4:5] op_sel_hi:[1,0,1]
	v_pk_fma_f32 v[10:11], v[46:47], v[152:153], v[10:11] op_sel:[0,1,0]
	v_pk_fma_f32 v[12:13], v[48:49], v[152:153], v[12:13] op_sel:[0,1,0]
	v_pk_fma_f32 v[14:15], v[46:47], v[154:155], v[14:15] op_sel_hi:[1,0,1]
	v_pk_fma_f32 v[16:17], v[48:49], v[154:155], v[16:17] op_sel_hi:[1,0,1]
	v_pk_fma_f32 v[6:7], v[46:47], v[154:155], v[6:7] op_sel:[0,1,0]
	v_pk_fma_f32 v[8:9], v[48:49], v[154:155], v[8:9] op_sel:[0,1,0]
	v_pk_fma_f32 v[18:19], v[46:47], v[156:157], v[18:19] op_sel_hi:[1,0,1]
	v_pk_fma_f32 v[20:21], v[48:49], v[156:157], v[20:21] op_sel_hi:[1,0,1]
	v_pk_fma_f32 v[26:27], v[46:47], v[156:157], v[26:27] op_sel:[0,1,0]
	v_pk_fma_f32 v[28:29], v[48:49], v[156:157], v[28:29] op_sel:[0,1,0]
	v_pk_fma_f32 v[30:31], v[46:47], v[158:159], v[30:31] op_sel_hi:[1,0,1]
	v_pk_fma_f32 v[32:33], v[48:49], v[158:159], v[32:33] op_sel_hi:[1,0,1]
	v_pk_fma_f32 v[22:23], v[46:47], v[158:159], v[22:23] op_sel:[0,1,0]
	v_pk_fma_f32 v[24:25], v[48:49], v[158:159], v[24:25] op_sel:[0,1,0]
	s_waitcnt lgkmcnt(0)
	ds_read_b128 v[152:155], v78 offset:1184
	ds_read_b128 v[156:159], v78 offset:1200
	s_waitcnt vmcnt(27)
	v_pk_fma_f32 v[2:3], v[50:51], v[144:145], v[2:3] op_sel_hi:[1,0,1]
	v_pk_fma_f32 v[4:5], v[52:53], v[144:145], v[4:5] op_sel_hi:[1,0,1]
	v_pk_fma_f32 v[10:11], v[50:51], v[144:145], v[10:11] op_sel:[0,1,0]
	v_pk_fma_f32 v[12:13], v[52:53], v[144:145], v[12:13] op_sel:[0,1,0]
	v_pk_fma_f32 v[14:15], v[50:51], v[146:147], v[14:15] op_sel_hi:[1,0,1]
	v_pk_fma_f32 v[16:17], v[52:53], v[146:147], v[16:17] op_sel_hi:[1,0,1]
	v_pk_fma_f32 v[6:7], v[50:51], v[146:147], v[6:7] op_sel:[0,1,0]
	v_pk_fma_f32 v[8:9], v[52:53], v[146:147], v[8:9] op_sel:[0,1,0]
	v_pk_fma_f32 v[18:19], v[50:51], v[148:149], v[18:19] op_sel_hi:[1,0,1]
	v_pk_fma_f32 v[20:21], v[52:53], v[148:149], v[20:21] op_sel_hi:[1,0,1]
	v_pk_fma_f32 v[26:27], v[50:51], v[148:149], v[26:27] op_sel:[0,1,0]
	v_pk_fma_f32 v[28:29], v[52:53], v[148:149], v[28:29] op_sel:[0,1,0]
	v_pk_fma_f32 v[30:31], v[50:51], v[150:151], v[30:31] op_sel_hi:[1,0,1]
	v_pk_fma_f32 v[32:33], v[52:53], v[150:151], v[32:33] op_sel_hi:[1,0,1]
	v_pk_fma_f32 v[22:23], v[50:51], v[150:151], v[22:23] op_sel:[0,1,0]
	v_pk_fma_f32 v[24:25], v[52:53], v[150:151], v[24:25] op_sel:[0,1,0]
	s_waitcnt lgkmcnt(0)
	ds_read_b128 v[144:147], v78 offset:1216
	ds_read_b128 v[148:151], v78 offset:1232
	s_waitcnt vmcnt(26)
	v_pk_fma_f32 v[2:3], v[54:55], v[152:153], v[2:3] op_sel_hi:[1,0,1]
	v_pk_fma_f32 v[4:5], v[56:57], v[152:153], v[4:5] op_sel_hi:[1,0,1]
	v_pk_fma_f32 v[10:11], v[54:55], v[152:153], v[10:11] op_sel:[0,1,0]
	v_pk_fma_f32 v[12:13], v[56:57], v[152:153], v[12:13] op_sel:[0,1,0]
	v_pk_fma_f32 v[14:15], v[54:55], v[154:155], v[14:15] op_sel_hi:[1,0,1]
	v_pk_fma_f32 v[16:17], v[56:57], v[154:155], v[16:17] op_sel_hi:[1,0,1]
	v_pk_fma_f32 v[6:7], v[54:55], v[154:155], v[6:7] op_sel:[0,1,0]
	v_pk_fma_f32 v[8:9], v[56:57], v[154:155], v[8:9] op_sel:[0,1,0]
	v_pk_fma_f32 v[18:19], v[54:55], v[156:157], v[18:19] op_sel_hi:[1,0,1]
	v_pk_fma_f32 v[20:21], v[56:57], v[156:157], v[20:21] op_sel_hi:[1,0,1]
	v_pk_fma_f32 v[26:27], v[54:55], v[156:157], v[26:27] op_sel:[0,1,0]
	v_pk_fma_f32 v[28:29], v[56:57], v[156:157], v[28:29] op_sel:[0,1,0]
	v_pk_fma_f32 v[30:31], v[54:55], v[158:159], v[30:31] op_sel_hi:[1,0,1]
	v_pk_fma_f32 v[32:33], v[56:57], v[158:159], v[32:33] op_sel_hi:[1,0,1]
	v_pk_fma_f32 v[22:23], v[54:55], v[158:159], v[22:23] op_sel:[0,1,0]
	v_pk_fma_f32 v[24:25], v[56:57], v[158:159], v[24:25] op_sel:[0,1,0]
	s_waitcnt lgkmcnt(0)
	ds_read_b128 v[152:155], v78 offset:1248
	ds_read_b128 v[156:159], v78 offset:1264
	s_waitcnt vmcnt(25)
	v_pk_fma_f32 v[2:3], v[58:59], v[144:145], v[2:3] op_sel_hi:[1,0,1]
	v_pk_fma_f32 v[4:5], v[60:61], v[144:145], v[4:5] op_sel_hi:[1,0,1]
	v_pk_fma_f32 v[10:11], v[58:59], v[144:145], v[10:11] op_sel:[0,1,0]
	v_pk_fma_f32 v[12:13], v[60:61], v[144:145], v[12:13] op_sel:[0,1,0]
	v_pk_fma_f32 v[14:15], v[58:59], v[146:147], v[14:15] op_sel_hi:[1,0,1]
	v_pk_fma_f32 v[16:17], v[60:61], v[146:147], v[16:17] op_sel_hi:[1,0,1]
	v_pk_fma_f32 v[6:7], v[58:59], v[146:147], v[6:7] op_sel:[0,1,0]
	v_pk_fma_f32 v[8:9], v[60:61], v[146:147], v[8:9] op_sel:[0,1,0]
	v_pk_fma_f32 v[18:19], v[58:59], v[148:149], v[18:19] op_sel_hi:[1,0,1]
	v_pk_fma_f32 v[20:21], v[60:61], v[148:149], v[20:21] op_sel_hi:[1,0,1]
	v_pk_fma_f32 v[26:27], v[58:59], v[148:149], v[26:27] op_sel:[0,1,0]
	v_pk_fma_f32 v[28:29], v[60:61], v[148:149], v[28:29] op_sel:[0,1,0]
	v_pk_fma_f32 v[30:31], v[58:59], v[150:151], v[30:31] op_sel_hi:[1,0,1]
	v_pk_fma_f32 v[32:33], v[60:61], v[150:151], v[32:33] op_sel_hi:[1,0,1]
	v_pk_fma_f32 v[22:23], v[58:59], v[150:151], v[22:23] op_sel:[0,1,0]
	v_pk_fma_f32 v[24:25], v[60:61], v[150:151], v[24:25] op_sel:[0,1,0]
	s_waitcnt lgkmcnt(0)
; #define LAS __attribute__((address_space(3)))
; __device__ __forceinline__ void mod_item(int item, const float* w_ada, const float* b_ada, float* mod, LAS unsigned char* lds, int tid) {
;     ...
;     const float* wp = w_ada + ((size_t)layer * 2048 + ks * 64) * 6144 + col0 + quad * 4;
;     f32x4 a0 = {0, 0, 0, 0}, a1 = a0, a2 = a0, a3 = a0, a4 = a0, a5 = a0, a6 = a0, a7 = a0;
; #pragma unroll 8
;     for (int kk = 0; kk < 64; ++kk) {
;         const f32x4 w = *(const f32x4*)(wp + (size_t)kk * 6144);
;         const f32x4 c0 = *(const LAS f32x4*)(cond + (ks * 64 + kk) * 8), c1 = *(const LAS f32x4*)(cond + (ks * 64 + kk) * 8 + 4);
;         a0 += c0[0] * w; a1 += c0[1] * w; a2 += c0[2] * w; a3 += c0[3] * w; a4 += c1[0] * w; a5 += c1[1] * w; a6 += c1[2] * w; a7 += c1[3] * w;
;     }
	ds_read_b128 v[144:147], v78 offset:1280
	ds_read_b128 v[148:151], v78 offset:1296
	s_waitcnt vmcnt(24)
	v_pk_fma_f32 v[2:3], v[62:63], v[152:153], v[2:3] op_sel_hi:[1,0,1]
	v_pk_fma_f32 v[4:5], v[64:65], v[152:153], v[4:5] op_sel_hi:[1,0,1]
	v_pk_fma_f32 v[10:11], v[62:63], v[152:153], v[10:11] op_sel:[0,1,0]
	v_pk_fma_f32 v[12:13], v[64:65], v[152:153], v[12:13] op_sel:[0,1,0]
	v_pk_fma_f32 v[14:15], v[62:63], v[154:155], v[14:15] op_sel_hi:[1,0,1]
	v_pk_fma_f32 v[16:17], v[64:65], v[154:155], v[16:17] op_sel_hi:[1,0,1]
	v_pk_fma_f32 v[6:7], v[62:63], v[154:155], v[6:7] op_sel:[0,1,0]
	v_pk_fma_f32 v[8:9], v[64:65], v[154:155], v[8:9] op_sel:[0,1,0]
	v_pk_fma_f32 v[18:19], v[62:63], v[156:157], v[18:19] op_sel_hi:[1,0,1]
	v_pk_fma_f32 v[20:21], v[64:65], v[156:157], v[20:21] op_sel_hi:[1,0,1]
	v_pk_fma_f32 v[26:27], v[62:63], v[156:157], v[26:27] op_sel:[0,1,0]
	v_pk_fma_f32 v[28:29], v[64:65], v[156:157], v[28:29] op_sel:[0,1,0]
	v_pk_fma_f32 v[30:31], v[62:63], v[158:159], v[30:31] op_sel_hi:[1,0,1]
	v_pk_fma_f32 v[32:33], v[64:65], v[158:159], v[32:33] op_sel_hi:[1,0,1]
	v_pk_fma_f32 v[22:23], v[62:63], v[158:159], v[22:23] op_sel:[0,1,0]
	v_pk_fma_f32 v[24:25], v[64:65], v[158:159], v[24:25] op_sel:[0,1,0]
	s_waitcnt lgkmcnt(0)
	ds_read_b128 v[152:155], v78 offset:1312
	ds_read_b128 v[156:159], v78 offset:1328
	s_waitcnt vmcnt(23)
	v_pk_fma_f32 v[2:3], v[80:81], v[144:145], v[2:3] op_sel_hi:[1,0,1]
	v_pk_fma_f32 v[4:5], v[82:83], v[144:145], v[4:5] op_sel_hi:[1,0,1]
	v_pk_fma_f32 v[10:11], v[80:81], v[144:145], v[10:11] op_sel:[0,1,0]
	v_pk_fma_f32 v[12:13], v[82:83], v[144:145], v[12:13] op_sel:[0,1,0]
	v_pk_fma_f32 v[14:15], v[80:81], v[146:147], v[14:15] op_sel_hi:[1,0,1]
	v_pk_fma_f32 v[16:17], v[82:83], v[146:147], v[16:17] op_sel_hi:[1,0,1]
	v_pk_fma_f32 v[6:7], v[80:81], v[146:147], v[6:7] op_sel:[0,1,0]
	v_pk_fma_f32 v[8:9], v[82:83], v[146:147], v[8:9] op_sel:[0,1,0]
	v_pk_fma_f32 v[18:19], v[80:81], v[148:149], v[18:19] op_sel_hi:[1,0,1]
	v_pk_fma_f32 v[20:21], v[82:83], v[148:149], v[20:21] op_sel_hi:[1,0,1]
	v_pk_fma_f32 v[26:27], v[80:81], v[148:149], v[26:27] op_sel:[0,1,0]
	v_pk_fma_f32 v[28:29], v[82:83], v[148:149], v[28:29] op_sel:[0,1,0]
	v_pk_fma_f32 v[30:31], v[80:81], v[150:151], v[30:31] op_sel_hi:[1,0,1]
	v_pk_fma_f32 v[32:33], v[82:83], v[150:151], v[32:33] op_sel_hi:[1,0,1]
	v_pk_fma_f32 v[22:23], v[80:81], v[150:151], v[22:23] op_sel:[0,1,0]
	v_pk_fma_f32 v[24:25], v[82:83], v[150:151], v[24:25] op_sel:[0,1,0]
	s_waitcnt lgkmcnt(0)
	ds_read_b128 v[144:147], v78 offset:1344
	ds_read_b128 v[148:151], v78 offset:1360
	s_waitcnt vmcnt(22)
	v_pk_fma_f32 v[2:3], v[84:85], v[152:153], v[2:3] op_sel_hi:[1,0,1]
	v_pk_fma_f32 v[4:5], v[86:87], v[152:153], v[4:5] op_sel_hi:[1,0,1]
	v_pk_fma_f32 v[10:11], v[84:85], v[152:153], v[10:11] op_sel:[0,1,0]
	v_pk_fma_f32 v[12:13], v[86:87], v[152:153], v[12:13] op_sel:[0,1,0]
	v_pk_fma_f32 v[14:15], v[84:85], v[154:155], v[14:15] op_sel_hi:[1,0,1]
	v_pk_fma_f32 v[16:17], v[86:87], v[154:155], v[16:17] op_sel_hi:[1,0,1]
	v_pk_fma_f32 v[6:7], v[84:85], v[154:155], v[6:7] op_sel:[0,1,0]
	v_pk_fma_f32 v[8:9], v[86:87], v[154:155], v[8:9] op_sel:[0,1,0]
	v_pk_fma_f32 v[18:19], v[84:85], v[156:157], v[18:19] op_sel_hi:[1,0,1]
	v_pk_fma_f32 v[20:21], v[86:87], v[156:157], v[20:21] op_sel_hi:[1,0,1]
	v_pk_fma_f32 v[26:27], v[84:85], v[156:157], v[26:27] op_sel:[0,1,0]
	v_pk_fma_f32 v[28:29], v[86:87], v[156:157], v[28:29] op_sel:[0,1,0]
	v_pk_fma_f32 v[30:31], v[84:85], v[158:159], v[30:31] op_sel_hi:[1,0,1]
	v_pk_fma_f32 v[32:33], v[86:87], v[158:159], v[32:33] op_sel_hi:[1,0,1]
	v_pk_fma_f32 v[22:23], v[84:85], v[158:159], v[22:23] op_sel:[0,1,0]
	v_pk_fma_f32 v[24:25], v[86:87], v[158:159], v[24:25] op_sel:[0,1,0]
	s_waitcnt lgkmcnt(0)
	ds_read_b128 v[152:155], v78 offset:1376
	ds_read_b128 v[156:159], v78 offset:1392
	s_waitcnt vmcnt(21)
	v_pk_fma_f32 v[2:3], v[88:89], v[144:145], v[2:3] op_sel_hi:[1,0,1]
	v_pk_fma_f32 v[4:5], v[90:91], v[144:145], v[4:5] op_sel_hi:[1,0,1]
	v_pk_fma_f32 v[10:11], v[88:89], v[144:145], v[10:11] op_sel:[0,1,0]
	v_pk_fma_f32 v[12:13], v[90:91], v[144:145], v[12:13] op_sel:[0,1,0]
	v_pk_fma_f32 v[14:15], v[88:89], v[146:147], v[14:15] op_sel_hi:[1,0,1]
	v_pk_fma_f32 v[16:17], v[90:91], v[146:147], v[16:17] op_sel_hi:[1,0,1]
	v_pk_fma_f32 v[6:7], v[88:89], v[146:147], v[6:7] op_sel:[0,1,0]
	v_pk_fma_f32 v[8:9], v[90:91], v[146:147], v[8:9] op_sel:[0,1,0]
	v_pk_fma_f32 v[18:19], v[88:89], v[148:149], v[18:19] op_sel_hi:[1,0,1]
	v_pk_fma_f32 v[20:21], v[90:91], v[148:149], v[20:21] op_sel_hi:[1,0,1]
	v_pk_fma_f32 v[26:27], v[88:89], v[148:149], v[26:27] op_sel:[0,1,0]
	v_pk_fma_f32 v[28:29], v[90:91], v[148:149], v[28:29] op_sel:[0,1,0]
	v_pk_fma_f32 v[30:31], v[88:89], v[150:151], v[30:31] op_sel_hi:[1,0,1]
	v_pk_fma_f32 v[32:33], v[90:91], v[150:151], v[32:33] op_sel_hi:[1,0,1]
	v_pk_fma_f32 v[22:23], v[88:89], v[150:151], v[22:23] op_sel:[0,1,0]
	v_pk_fma_f32 v[24:25], v[90:91], v[150:151], v[24:25] op_sel:[0,1,0]
	s_waitcnt lgkmcnt(0)
	ds_read_b128 v[144:147], v78 offset:1408
	ds_read_b128 v[148:151], v78 offset:1424
	s_waitcnt vmcnt(20)
; #define LAS __attribute__((address_space(3)))
; __device__ __forceinline__ void mod_item(int item, const float* w_ada, const float* b_ada, float* mod, LAS unsigned char* lds, int tid) {
;     ...
;     const float* wp = w_ada + ((size_t)layer * 2048 + ks * 64) * 6144 + col0 + quad * 4;
;     f32x4 a0 = {0, 0, 0, 0}, a1 = a0, a2 = a0, a3 = a0, a4 = a0, a5 = a0, a6 = a0, a7 = a0;
; #pragma unroll 8
;     for (int kk = 0; kk < 64; ++kk) {
;         const f32x4 w = *(const f32x4*)(wp + (size_t)kk * 6144);
;         const f32x4 c0 = *(const LAS f32x4*)(cond + (ks * 64 + kk) * 8), c1 = *(const LAS f32x4*)(cond + (ks * 64 + kk) * 8 + 4);
;         a0 += c0[0] * w; a1 += c0[1] * w; a2 += c0[2] * w; a3 += c0[3] * w; a4 += c1[0] * w; a5 += c1[1] * w; a6 += c1[2] * w; a7 += c1[3] * w;
;     }
	v_pk_fma_f32 v[2:3], v[92:93], v[152:153], v[2:3] op_sel_hi:[1,0,1]
	v_pk_fma_f32 v[4:5], v[94:95], v[152:153], v[4:5] op_sel_hi:[1,0,1]
	v_pk_fma_f32 v[10:11], v[92:93], v[152:153], v[10:11] op_sel:[0,1,0]
	v_pk_fma_f32 v[12:13], v[94:95], v[152:153], v[12:13] op_sel:[0,1,0]
	v_pk_fma_f32 v[14:15], v[92:93], v[154:155], v[14:15] op_sel_hi:[1,0,1]
	v_pk_fma_f32 v[16:17], v[94:95], v[154:155], v[16:17] op_sel_hi:[1,0,1]
	v_pk_fma_f32 v[6:7], v[92:93], v[154:155], v[6:7] op_sel:[0,1,0]
	v_pk_fma_f32 v[8:9], v[94:95], v[154:155], v[8:9] op_sel:[0,1,0]
	v_pk_fma_f32 v[18:19], v[92:93], v[156:157], v[18:19] op_sel_hi:[1,0,1]
	v_pk_fma_f32 v[20:21], v[94:95], v[156:157], v[20:21] op_sel_hi:[1,0,1]
	v_pk_fma_f32 v[26:27], v[92:93], v[156:157], v[26:27] op_sel:[0,1,0]
	v_pk_fma_f32 v[28:29], v[94:95], v[156:157], v[28:29] op_sel:[0,1,0]
	v_pk_fma_f32 v[30:31], v[92:93], v[158:159], v[30:31] op_sel_hi:[1,0,1]
	v_pk_fma_f32 v[32:33], v[94:95], v[158:159], v[32:33] op_sel_hi:[1,0,1]
	v_pk_fma_f32 v[22:23], v[92:93], v[158:159], v[22:23] op_sel:[0,1,0]
	v_pk_fma_f32 v[24:25], v[94:95], v[158:159], v[24:25] op_sel:[0,1,0]
	s_waitcnt lgkmcnt(0)
	ds_read_b128 v[152:155], v78 offset:1440
	ds_read_b128 v[156:159], v78 offset:1456
	s_waitcnt vmcnt(19)
	v_pk_fma_f32 v[2:3], v[96:97], v[144:145], v[2:3] op_sel_hi:[1,0,1]
	v_pk_fma_f32 v[4:5], v[98:99], v[144:145], v[4:5] op_sel_hi:[1,0,1]
	v_pk_fma_f32 v[10:11], v[96:97], v[144:145], v[10:11] op_sel:[0,1,0]
	v_pk_fma_f32 v[12:13], v[98:99], v[144:145], v[12:13] op_sel:[0,1,0]
	v_pk_fma_f32 v[14:15], v[96:97], v[146:147], v[14:15] op_sel_hi:[1,0,1]
	v_pk_fma_f32 v[16:17], v[98:99], v[146:147], v[16:17] op_sel_hi:[1,0,1]
	v_pk_fma_f32 v[6:7], v[96:97], v[146:147], v[6:7] op_sel:[0,1,0]
	v_pk_fma_f32 v[8:9], v[98:99], v[146:147], v[8:9] op_sel:[0,1,0]
	v_pk_fma_f32 v[18:19], v[96:97], v[148:149], v[18:19] op_sel_hi:[1,0,1]
	v_pk_fma_f32 v[20:21], v[98:99], v[148:149], v[20:21] op_sel_hi:[1,0,1]
	v_pk_fma_f32 v[26:27], v[96:97], v[148:149], v[26:27] op_sel:[0,1,0]
	v_pk_fma_f32 v[28:29], v[98:99], v[148:149], v[28:29] op_sel:[0,1,0]
	v_pk_fma_f32 v[30:31], v[96:97], v[150:151], v[30:31] op_sel_hi:[1,0,1]
	v_pk_fma_f32 v[32:33], v[98:99], v[150:151], v[32:33] op_sel_hi:[1,0,1]
	v_pk_fma_f32 v[22:23], v[96:97], v[150:151], v[22:23] op_sel:[0,1,0]
	v_pk_fma_f32 v[24:25], v[98:99], v[150:151], v[24:25] op_sel:[0,1,0]
	s_waitcnt lgkmcnt(0)
	ds_read_b128 v[144:147], v78 offset:1472
	ds_read_b128 v[148:151], v78 offset:1488
	s_waitcnt vmcnt(18)
	v_pk_fma_f32 v[2:3], v[100:101], v[152:153], v[2:3] op_sel_hi:[1,0,1]
	v_pk_fma_f32 v[4:5], v[102:103], v[152:153], v[4:5] op_sel_hi:[1,0,1]
	v_pk_fma_f32 v[10:11], v[100:101], v[152:153], v[10:11] op_sel:[0,1,0]
	v_pk_fma_f32 v[12:13], v[102:103], v[152:153], v[12:13] op_sel:[0,1,0]
	v_pk_fma_f32 v[14:15], v[100:101], v[154:155], v[14:15] op_sel_hi:[1,0,1]
	v_pk_fma_f32 v[16:17], v[102:103], v[154:155], v[16:17] op_sel_hi:[1,0,1]
	v_pk_fma_f32 v[6:7], v[100:101], v[154:155], v[6:7] op_sel:[0,1,0]
	v_pk_fma_f32 v[8:9], v[102:103], v[154:155], v[8:9] op_sel:[0,1,0]
	v_pk_fma_f32 v[18:19], v[100:101], v[156:157], v[18:19] op_sel_hi:[1,0,1]
	v_pk_fma_f32 v[20:21], v[102:103], v[156:157], v[20:21] op_sel_hi:[1,0,1]
	v_pk_fma_f32 v[26:27], v[100:101], v[156:157], v[26:27] op_sel:[0,1,0]
	v_pk_fma_f32 v[28:29], v[102:103], v[156:157], v[28:29] op_sel:[0,1,0]
	v_pk_fma_f32 v[30:31], v[100:101], v[158:159], v[30:31] op_sel_hi:[1,0,1]
	v_pk_fma_f32 v[32:33], v[102:103], v[158:159], v[32:33] op_sel_hi:[1,0,1]
	v_pk_fma_f32 v[22:23], v[100:101], v[158:159], v[22:23] op_sel:[0,1,0]
	v_pk_fma_f32 v[24:25], v[102:103], v[158:159], v[24:25] op_sel:[0,1,0]
	s_waitcnt lgkmcnt(0)
	ds_read_b128 v[152:155], v78 offset:1504
	ds_read_b128 v[156:159], v78 offset:1520
	s_waitcnt vmcnt(17)
	v_pk_fma_f32 v[2:3], v[104:105], v[144:145], v[2:3] op_sel_hi:[1,0,1]
	v_pk_fma_f32 v[4:5], v[106:107], v[144:145], v[4:5] op_sel_hi:[1,0,1]
	v_pk_fma_f32 v[10:11], v[104:105], v[144:145], v[10:11] op_sel:[0,1,0]
	v_pk_fma_f32 v[12:13], v[106:107], v[144:145], v[12:13] op_sel:[0,1,0]
	v_pk_fma_f32 v[14:15], v[104:105], v[146:147], v[14:15] op_sel_hi:[1,0,1]
	v_pk_fma_f32 v[16:17], v[106:107], v[146:147], v[16:17] op_sel_hi:[1,0,1]
	v_pk_fma_f32 v[6:7], v[104:105], v[146:147], v[6:7] op_sel:[0,1,0]
	v_pk_fma_f32 v[8:9], v[106:107], v[146:147], v[8:9] op_sel:[0,1,0]
	v_pk_fma_f32 v[18:19], v[104:105], v[148:149], v[18:19] op_sel_hi:[1,0,1]
	v_pk_fma_f32 v[20:21], v[106:107], v[148:149], v[20:21] op_sel_hi:[1,0,1]
	v_pk_fma_f32 v[26:27], v[104:105], v[148:149], v[26:27] op_sel:[0,1,0]
	v_pk_fma_f32 v[28:29], v[106:107], v[148:149], v[28:29] op_sel:[0,1,0]
	v_pk_fma_f32 v[30:31], v[104:105], v[150:151], v[30:31] op_sel_hi:[1,0,1]
	v_pk_fma_f32 v[32:33], v[106:107], v[150:151], v[32:33] op_sel_hi:[1,0,1]
	v_pk_fma_f32 v[22:23], v[104:105], v[150:151], v[22:23] op_sel:[0,1,0]
	v_pk_fma_f32 v[24:25], v[106:107], v[150:151], v[24:25] op_sel:[0,1,0]
	s_waitcnt lgkmcnt(0)
	ds_read_b128 v[144:147], v78 offset:1536
	ds_read_b128 v[148:151], v78 offset:1552
	s_waitcnt vmcnt(16)
; #define LAS __attribute__((address_space(3)))
; __device__ __forceinline__ void mod_item(int item, const float* w_ada, const float* b_ada, float* mod, LAS unsigned char* lds, int tid) {
;     ...
;     const float* wp = w_ada + ((size_t)layer * 2048 + ks * 64) * 6144 + col0 + quad * 4;
;     f32x4 a0 = {0, 0, 0, 0}, a1 = a0, a2 = a0, a3 = a0, a4 = a0, a5 = a0, a6 = a0, a7 = a0;
; #pragma unroll 8
;     for (int kk = 0; kk < 64; ++kk) {
;         const f32x4 w = *(const f32x4*)(wp + (size_t)kk * 6144);
;         const f32x4 c0 = *(const LAS f32x4*)(cond + (ks * 64 + kk) * 8), c1 = *(const LAS f32x4*)(cond + (ks * 64 + kk) * 8 + 4);
;         a0 += c0[0] * w; a1 += c0[1] * w; a2 += c0[2] * w; a3 += c0[3] * w; a4 += c1[0] * w; a5 += c1[1] * w; a6 += c1[2] * w; a7 += c1[3] * w;
;     }
	v_pk_fma_f32 v[2:3], v[108:109], v[152:153], v[2:3] op_sel_hi:[1,0,1]
	v_pk_fma_f32 v[4:5], v[110:111], v[152:153], v[4:5] op_sel_hi:[1,0,1]
	v_pk_fma_f32 v[10:11], v[108:109], v[152:153], v[10:11] op_sel:[0,1,0]
	v_pk_fma_f32 v[12:13], v[110:111], v[152:153], v[12:13] op_sel:[0,1,0]
	v_pk_fma_f32 v[14:15], v[108:109], v[154:155], v[14:15] op_sel_hi:[1,0,1]
	v_pk_fma_f32 v[16:17], v[110:111], v[154:155], v[16:17] op_sel_hi:[1,0,1]
	v_pk_fma_f32 v[6:7], v[108:109], v[154:155], v[6:7] op_sel:[0,1,0]
	v_pk_fma_f32 v[8:9], v[110:111], v[154:155], v[8:9] op_sel:[0,1,0]
	v_pk_fma_f32 v[18:19], v[108:109], v[156:157], v[18:19] op_sel_hi:[1,0,1]
	v_pk_fma_f32 v[20:21], v[110:111], v[156:157], v[20:21] op_sel_hi:[1,0,1]
	v_pk_fma_f32 v[26:27], v[108:109], v[156:157], v[26:27] op_sel:[0,1,0]
	v_pk_fma_f32 v[28:29], v[110:111], v[156:157], v[28:29] op_sel:[0,1,0]
	v_pk_fma_f32 v[30:31], v[108:109], v[158:159], v[30:31] op_sel_hi:[1,0,1]
	v_pk_fma_f32 v[32:33], v[110:111], v[158:159], v[32:33] op_sel_hi:[1,0,1]
	v_pk_fma_f32 v[22:23], v[108:109], v[158:159], v[22:23] op_sel:[0,1,0]
	v_pk_fma_f32 v[24:25], v[110:111], v[158:159], v[24:25] op_sel:[0,1,0]
	s_waitcnt lgkmcnt(0)
	ds_read_b128 v[152:155], v78 offset:1568
	ds_read_b128 v[156:159], v78 offset:1584
	s_waitcnt vmcnt(15)
	v_pk_fma_f32 v[2:3], v[112:113], v[144:145], v[2:3] op_sel_hi:[1,0,1]
	v_pk_fma_f32 v[4:5], v[114:115], v[144:145], v[4:5] op_sel_hi:[1,0,1]
	v_pk_fma_f32 v[10:11], v[112:113], v[144:145], v[10:11] op_sel:[0,1,0]
	v_pk_fma_f32 v[12:13], v[114:115], v[144:145], v[12:13] op_sel:[0,1,0]
	v_pk_fma_f32 v[14:15], v[112:113], v[146:147], v[14:15] op_sel_hi:[1,0,1]
	v_pk_fma_f32 v[16:17], v[114:115], v[146:147], v[16:17] op_sel_hi:[1,0,1]
	v_pk_fma_f32 v[6:7], v[112:113], v[146:147], v[6:7] op_sel:[0,1,0]
	v_pk_fma_f32 v[8:9], v[114:115], v[146:147], v[8:9] op_sel:[0,1,0]
	v_pk_fma_f32 v[18:19], v[112:113], v[148:149], v[18:19] op_sel_hi:[1,0,1]
	v_pk_fma_f32 v[20:21], v[114:115], v[148:149], v[20:21] op_sel_hi:[1,0,1]
	v_pk_fma_f32 v[26:27], v[112:113], v[148:149], v[26:27] op_sel:[0,1,0]
	v_pk_fma_f32 v[28:29], v[114:115], v[148:149], v[28:29] op_sel:[0,1,0]
	v_pk_fma_f32 v[30:31], v[112:113], v[150:151], v[30:31] op_sel_hi:[1,0,1]
	v_pk_fma_f32 v[32:33], v[114:115], v[150:151], v[32:33] op_sel_hi:[1,0,1]
	v_pk_fma_f32 v[22:23], v[112:113], v[150:151], v[22:23] op_sel:[0,1,0]
	v_pk_fma_f32 v[24:25], v[114:115], v[150:151], v[24:25] op_sel:[0,1,0]
	s_waitcnt lgkmcnt(0)
	ds_read_b128 v[144:147], v78 offset:1600
	ds_read_b128 v[148:151], v78 offset:1616
	s_waitcnt vmcnt(14)
	v_pk_fma_f32 v[2:3], v[116:117], v[152:153], v[2:3] op_sel_hi:[1,0,1]
	v_pk_fma_f32 v[4:5], v[118:119], v[152:153], v[4:5] op_sel_hi:[1,0,1]
	v_pk_fma_f32 v[10:11], v[116:117], v[152:153], v[10:11] op_sel:[0,1,0]
	v_pk_fma_f32 v[12:13], v[118:119], v[152:153], v[12:13] op_sel:[0,1,0]
	v_pk_fma_f32 v[14:15], v[116:117], v[154:155], v[14:15] op_sel_hi:[1,0,1]
	v_pk_fma_f32 v[16:17], v[118:119], v[154:155], v[16:17] op_sel_hi:[1,0,1]
	v_pk_fma_f32 v[6:7], v[116:117], v[154:155], v[6:7] op_sel:[0,1,0]
	v_pk_fma_f32 v[8:9], v[118:119], v[154:155], v[8:9] op_sel:[0,1,0]
	v_pk_fma_f32 v[18:19], v[116:117], v[156:157], v[18:19] op_sel_hi:[1,0,1]
	v_pk_fma_f32 v[20:21], v[118:119], v[156:157], v[20:21] op_sel_hi:[1,0,1]
	v_pk_fma_f32 v[26:27], v[116:117], v[156:157], v[26:27] op_sel:[0,1,0]
	v_pk_fma_f32 v[28:29], v[118:119], v[156:157], v[28:29] op_sel:[0,1,0]
	v_pk_fma_f32 v[30:31], v[116:117], v[158:159], v[30:31] op_sel_hi:[1,0,1]
	v_pk_fma_f32 v[32:33], v[118:119], v[158:159], v[32:33] op_sel_hi:[1,0,1]
	v_pk_fma_f32 v[22:23], v[116:117], v[158:159], v[22:23] op_sel:[0,1,0]
	v_pk_fma_f32 v[24:25], v[118:119], v[158:159], v[24:25] op_sel:[0,1,0]
	s_waitcnt lgkmcnt(0)
	ds_read_b128 v[152:155], v78 offset:1632
	ds_read_b128 v[156:159], v78 offset:1648
	s_waitcnt vmcnt(13)
	v_pk_fma_f32 v[2:3], v[120:121], v[144:145], v[2:3] op_sel_hi:[1,0,1]
	v_pk_fma_f32 v[4:5], v[122:123], v[144:145], v[4:5] op_sel_hi:[1,0,1]
	v_pk_fma_f32 v[10:11], v[120:121], v[144:145], v[10:11] op_sel:[0,1,0]
	v_pk_fma_f32 v[12:13], v[122:123], v[144:145], v[12:13] op_sel:[0,1,0]
	v_pk_fma_f32 v[14:15], v[120:121], v[146:147], v[14:15] op_sel_hi:[1,0,1]
	v_pk_fma_f32 v[16:17], v[122:123], v[146:147], v[16:17] op_sel_hi:[1,0,1]
	v_pk_fma_f32 v[6:7], v[120:121], v[146:147], v[6:7] op_sel:[0,1,0]
	v_pk_fma_f32 v[8:9], v[122:123], v[146:147], v[8:9] op_sel:[0,1,0]
	v_pk_fma_f32 v[18:19], v[120:121], v[148:149], v[18:19] op_sel_hi:[1,0,1]
	v_pk_fma_f32 v[20:21], v[122:123], v[148:149], v[20:21] op_sel_hi:[1,0,1]
	v_pk_fma_f32 v[26:27], v[120:121], v[148:149], v[26:27] op_sel:[0,1,0]
	v_pk_fma_f32 v[28:29], v[122:123], v[148:149], v[28:29] op_sel:[0,1,0]
	v_pk_fma_f32 v[30:31], v[120:121], v[150:151], v[30:31] op_sel_hi:[1,0,1]
	v_pk_fma_f32 v[32:33], v[122:123], v[150:151], v[32:33] op_sel_hi:[1,0,1]
	v_pk_fma_f32 v[22:23], v[120:121], v[150:151], v[22:23] op_sel:[0,1,0]
	v_pk_fma_f32 v[24:25], v[122:123], v[150:151], v[24:25] op_sel:[0,1,0]
	s_waitcnt lgkmcnt(0)
	ds_read_b128 v[144:147], v78 offset:1664
	ds_read_b128 v[148:151], v78 offset:1680
	s_waitcnt vmcnt(12)
; #define LAS __attribute__((address_space(3)))
; __device__ __forceinline__ void mod_item(int item, const float* w_ada, const float* b_ada, float* mod, LAS unsigned char* lds, int tid) {
;     ...
;     const float* wp = w_ada + ((size_t)layer * 2048 + ks * 64) * 6144 + col0 + quad * 4;
;     f32x4 a0 = {0, 0, 0, 0}, a1 = a0, a2 = a0, a3 = a0, a4 = a0, a5 = a0, a6 = a0, a7 = a0;
; #pragma unroll 8
;     for (int kk = 0; kk < 64; ++kk) {
;         const f32x4 w = *(const f32x4*)(wp + (size_t)kk * 6144);
;         const f32x4 c0 = *(const LAS f32x4*)(cond + (ks * 64 + kk) * 8), c1 = *(const LAS f32x4*)(cond + (ks * 64 + kk) * 8 + 4);
;         a0 += c0[0] * w; a1 += c0[1] * w; a2 += c0[2] * w; a3 += c0[3] * w; a4 += c1[0] * w; a5 += c1[1] * w; a6 += c1[2] * w; a7 += c1[3] * w;
;     }
	v_pk_fma_f32 v[2:3], v[124:125], v[152:153], v[2:3] op_sel_hi:[1,0,1]
	v_pk_fma_f32 v[4:5], v[126:127], v[152:153], v[4:5] op_sel_hi:[1,0,1]
	v_pk_fma_f32 v[10:11], v[124:125], v[152:153], v[10:11] op_sel:[0,1,0]
	v_pk_fma_f32 v[12:13], v[126:127], v[152:153], v[12:13] op_sel:[0,1,0]
	v_pk_fma_f32 v[14:15], v[124:125], v[154:155], v[14:15] op_sel_hi:[1,0,1]
	v_pk_fma_f32 v[16:17], v[126:127], v[154:155], v[16:17] op_sel_hi:[1,0,1]
	v_pk_fma_f32 v[6:7], v[124:125], v[154:155], v[6:7] op_sel:[0,1,0]
	v_pk_fma_f32 v[8:9], v[126:127], v[154:155], v[8:9] op_sel:[0,1,0]
	v_pk_fma_f32 v[18:19], v[124:125], v[156:157], v[18:19] op_sel_hi:[1,0,1]
	v_pk_fma_f32 v[20:21], v[126:127], v[156:157], v[20:21] op_sel_hi:[1,0,1]
	v_pk_fma_f32 v[26:27], v[124:125], v[156:157], v[26:27] op_sel:[0,1,0]
	v_pk_fma_f32 v[28:29], v[126:127], v[156:157], v[28:29] op_sel:[0,1,0]
	v_pk_fma_f32 v[30:31], v[124:125], v[158:159], v[30:31] op_sel_hi:[1,0,1]
	v_pk_fma_f32 v[32:33], v[126:127], v[158:159], v[32:33] op_sel_hi:[1,0,1]
	v_pk_fma_f32 v[22:23], v[124:125], v[158:159], v[22:23] op_sel:[0,1,0]
	v_pk_fma_f32 v[24:25], v[126:127], v[158:159], v[24:25] op_sel:[0,1,0]
	s_waitcnt lgkmcnt(0)
	ds_read_b128 v[152:155], v78 offset:1696
	ds_read_b128 v[156:159], v78 offset:1712
	s_waitcnt vmcnt(11)
	v_pk_fma_f32 v[2:3], v[128:129], v[144:145], v[2:3] op_sel_hi:[1,0,1]
	v_pk_fma_f32 v[4:5], v[130:131], v[144:145], v[4:5] op_sel_hi:[1,0,1]
	v_pk_fma_f32 v[10:11], v[128:129], v[144:145], v[10:11] op_sel:[0,1,0]
	v_pk_fma_f32 v[12:13], v[130:131], v[144:145], v[12:13] op_sel:[0,1,0]
	v_pk_fma_f32 v[14:15], v[128:129], v[146:147], v[14:15] op_sel_hi:[1,0,1]
	v_pk_fma_f32 v[16:17], v[130:131], v[146:147], v[16:17] op_sel_hi:[1,0,1]
	v_pk_fma_f32 v[6:7], v[128:129], v[146:147], v[6:7] op_sel:[0,1,0]
	v_pk_fma_f32 v[8:9], v[130:131], v[146:147], v[8:9] op_sel:[0,1,0]
	v_pk_fma_f32 v[18:19], v[128:129], v[148:149], v[18:19] op_sel_hi:[1,0,1]
	v_pk_fma_f32 v[20:21], v[130:131], v[148:149], v[20:21] op_sel_hi:[1,0,1]
	v_pk_fma_f32 v[26:27], v[128:129], v[148:149], v[26:27] op_sel:[0,1,0]
	v_pk_fma_f32 v[28:29], v[130:131], v[148:149], v[28:29] op_sel:[0,1,0]
	v_pk_fma_f32 v[30:31], v[128:129], v[150:151], v[30:31] op_sel_hi:[1,0,1]
	v_pk_fma_f32 v[32:33], v[130:131], v[150:151], v[32:33] op_sel_hi:[1,0,1]
	v_pk_fma_f32 v[22:23], v[128:129], v[150:151], v[22:23] op_sel:[0,1,0]
	v_pk_fma_f32 v[24:25], v[130:131], v[150:151], v[24:25] op_sel:[0,1,0]
	s_waitcnt lgkmcnt(0)
	ds_read_b128 v[144:147], v78 offset:1728
	ds_read_b128 v[148:151], v78 offset:1744
	s_waitcnt vmcnt(10)
	v_pk_fma_f32 v[2:3], v[132:133], v[152:153], v[2:3] op_sel_hi:[1,0,1]
	v_pk_fma_f32 v[4:5], v[134:135], v[152:153], v[4:5] op_sel_hi:[1,0,1]
	v_pk_fma_f32 v[10:11], v[132:133], v[152:153], v[10:11] op_sel:[0,1,0]
	v_pk_fma_f32 v[12:13], v[134:135], v[152:153], v[12:13] op_sel:[0,1,0]
	v_pk_fma_f32 v[14:15], v[132:133], v[154:155], v[14:15] op_sel_hi:[1,0,1]
	v_pk_fma_f32 v[16:17], v[134:135], v[154:155], v[16:17] op_sel_hi:[1,0,1]
	v_pk_fma_f32 v[6:7], v[132:133], v[154:155], v[6:7] op_sel:[0,1,0]
	v_pk_fma_f32 v[8:9], v[134:135], v[154:155], v[8:9] op_sel:[0,1,0]
	v_pk_fma_f32 v[18:19], v[132:133], v[156:157], v[18:19] op_sel_hi:[1,0,1]
	v_pk_fma_f32 v[20:21], v[134:135], v[156:157], v[20:21] op_sel_hi:[1,0,1]
	v_pk_fma_f32 v[26:27], v[132:133], v[156:157], v[26:27] op_sel:[0,1,0]
	v_pk_fma_f32 v[28:29], v[134:135], v[156:157], v[28:29] op_sel:[0,1,0]
	v_pk_fma_f32 v[30:31], v[132:133], v[158:159], v[30:31] op_sel_hi:[1,0,1]
	v_pk_fma_f32 v[32:33], v[134:135], v[158:159], v[32:33] op_sel_hi:[1,0,1]
	v_pk_fma_f32 v[22:23], v[132:133], v[158:159], v[22:23] op_sel:[0,1,0]
	v_pk_fma_f32 v[24:25], v[134:135], v[158:159], v[24:25] op_sel:[0,1,0]
	s_waitcnt lgkmcnt(0)
	ds_read_b128 v[152:155], v78 offset:1760
	ds_read_b128 v[156:159], v78 offset:1776
	s_waitcnt vmcnt(9)
	v_pk_fma_f32 v[2:3], v[136:137], v[144:145], v[2:3] op_sel_hi:[1,0,1]
	v_pk_fma_f32 v[4:5], v[138:139], v[144:145], v[4:5] op_sel_hi:[1,0,1]
	v_pk_fma_f32 v[10:11], v[136:137], v[144:145], v[10:11] op_sel:[0,1,0]
	v_pk_fma_f32 v[12:13], v[138:139], v[144:145], v[12:13] op_sel:[0,1,0]
	v_pk_fma_f32 v[14:15], v[136:137], v[146:147], v[14:15] op_sel_hi:[1,0,1]
	v_pk_fma_f32 v[16:17], v[138:139], v[146:147], v[16:17] op_sel_hi:[1,0,1]
	v_pk_fma_f32 v[6:7], v[136:137], v[146:147], v[6:7] op_sel:[0,1,0]
	v_pk_fma_f32 v[8:9], v[138:139], v[146:147], v[8:9] op_sel:[0,1,0]
	v_pk_fma_f32 v[18:19], v[136:137], v[148:149], v[18:19] op_sel_hi:[1,0,1]
	v_pk_fma_f32 v[20:21], v[138:139], v[148:149], v[20:21] op_sel_hi:[1,0,1]
	v_pk_fma_f32 v[26:27], v[136:137], v[148:149], v[26:27] op_sel:[0,1,0]
	v_pk_fma_f32 v[28:29], v[138:139], v[148:149], v[28:29] op_sel:[0,1,0]
	v_pk_fma_f32 v[30:31], v[136:137], v[150:151], v[30:31] op_sel_hi:[1,0,1]
	v_pk_fma_f32 v[32:33], v[138:139], v[150:151], v[32:33] op_sel_hi:[1,0,1]
	v_pk_fma_f32 v[22:23], v[136:137], v[150:151], v[22:23] op_sel:[0,1,0]
	v_pk_fma_f32 v[24:25], v[138:139], v[150:151], v[24:25] op_sel:[0,1,0]
	s_waitcnt lgkmcnt(0)
	ds_read_b128 v[144:147], v78 offset:1792
	ds_read_b128 v[148:151], v78 offset:1808
	s_waitcnt vmcnt(8)
; #define LAS __attribute__((address_space(3)))
; __device__ __forceinline__ void mod_item(int item, const float* w_ada, const float* b_ada, float* mod, LAS unsigned char* lds, int tid) {
;     ...
;     const float* wp = w_ada + ((size_t)layer * 2048 + ks * 64) * 6144 + col0 + quad * 4;
;     f32x4 a0 = {0, 0, 0, 0}, a1 = a0, a2 = a0, a3 = a0, a4 = a0, a5 = a0, a6 = a0, a7 = a0;
; #pragma unroll 8
;     for (int kk = 0; kk < 64; ++kk) {
;         const f32x4 w = *(const f32x4*)(wp + (size_t)kk * 6144);
;         const f32x4 c0 = *(const LAS f32x4*)(cond + (ks * 64 + kk) * 8), c1 = *(const LAS f32x4*)(cond + (ks * 64 + kk) * 8 + 4);
;         a0 += c0[0] * w; a1 += c0[1] * w; a2 += c0[2] * w; a3 += c0[3] * w; a4 += c1[0] * w; a5 += c1[1] * w; a6 += c1[2] * w; a7 += c1[3] * w;
;     }
	v_pk_fma_f32 v[2:3], v[140:141], v[152:153], v[2:3] op_sel_hi:[1,0,1]
	v_pk_fma_f32 v[4:5], v[142:143], v[152:153], v[4:5] op_sel_hi:[1,0,1]
	v_pk_fma_f32 v[10:11], v[140:141], v[152:153], v[10:11] op_sel:[0,1,0]
	v_pk_fma_f32 v[12:13], v[142:143], v[152:153], v[12:13] op_sel:[0,1,0]
	v_pk_fma_f32 v[14:15], v[140:141], v[154:155], v[14:15] op_sel_hi:[1,0,1]
	v_pk_fma_f32 v[16:17], v[142:143], v[154:155], v[16:17] op_sel_hi:[1,0,1]
	v_pk_fma_f32 v[6:7], v[140:141], v[154:155], v[6:7] op_sel:[0,1,0]
	v_pk_fma_f32 v[8:9], v[142:143], v[154:155], v[8:9] op_sel:[0,1,0]
	v_pk_fma_f32 v[18:19], v[140:141], v[156:157], v[18:19] op_sel_hi:[1,0,1]
	v_pk_fma_f32 v[20:21], v[142:143], v[156:157], v[20:21] op_sel_hi:[1,0,1]
	v_pk_fma_f32 v[26:27], v[140:141], v[156:157], v[26:27] op_sel:[0,1,0]
	v_pk_fma_f32 v[28:29], v[142:143], v[156:157], v[28:29] op_sel:[0,1,0]
	v_pk_fma_f32 v[30:31], v[140:141], v[158:159], v[30:31] op_sel_hi:[1,0,1]
	v_pk_fma_f32 v[32:33], v[142:143], v[158:159], v[32:33] op_sel_hi:[1,0,1]
	v_pk_fma_f32 v[22:23], v[140:141], v[158:159], v[22:23] op_sel:[0,1,0]
	v_pk_fma_f32 v[24:25], v[142:143], v[158:159], v[24:25] op_sel:[0,1,0]
	s_waitcnt lgkmcnt(0)
	ds_read_b128 v[152:155], v78 offset:1824
	ds_read_b128 v[156:159], v78 offset:1840
	s_waitcnt vmcnt(7)
	v_pk_fma_f32 v[2:3], v[176:177], v[144:145], v[2:3] op_sel_hi:[1,0,1]
	v_pk_fma_f32 v[4:5], v[178:179], v[144:145], v[4:5] op_sel_hi:[1,0,1]
	v_pk_fma_f32 v[10:11], v[176:177], v[144:145], v[10:11] op_sel:[0,1,0]
	v_pk_fma_f32 v[12:13], v[178:179], v[144:145], v[12:13] op_sel:[0,1,0]
	v_pk_fma_f32 v[14:15], v[176:177], v[146:147], v[14:15] op_sel_hi:[1,0,1]
	v_pk_fma_f32 v[16:17], v[178:179], v[146:147], v[16:17] op_sel_hi:[1,0,1]
	v_pk_fma_f32 v[6:7], v[176:177], v[146:147], v[6:7] op_sel:[0,1,0]
	v_pk_fma_f32 v[8:9], v[178:179], v[146:147], v[8:9] op_sel:[0,1,0]
	v_pk_fma_f32 v[18:19], v[176:177], v[148:149], v[18:19] op_sel_hi:[1,0,1]
	v_pk_fma_f32 v[20:21], v[178:179], v[148:149], v[20:21] op_sel_hi:[1,0,1]
	v_pk_fma_f32 v[26:27], v[176:177], v[148:149], v[26:27] op_sel:[0,1,0]
	v_pk_fma_f32 v[28:29], v[178:179], v[148:149], v[28:29] op_sel:[0,1,0]
	v_pk_fma_f32 v[30:31], v[176:177], v[150:151], v[30:31] op_sel_hi:[1,0,1]
	v_pk_fma_f32 v[32:33], v[178:179], v[150:151], v[32:33] op_sel_hi:[1,0,1]
	v_pk_fma_f32 v[22:23], v[176:177], v[150:151], v[22:23] op_sel:[0,1,0]
	v_pk_fma_f32 v[24:25], v[178:179], v[150:151], v[24:25] op_sel:[0,1,0]
	s_waitcnt lgkmcnt(0)
	ds_read_b128 v[144:147], v78 offset:1856
	ds_read_b128 v[148:151], v78 offset:1872
	s_waitcnt vmcnt(6)
	v_pk_fma_f32 v[2:3], v[180:181], v[152:153], v[2:3] op_sel_hi:[1,0,1]
	v_pk_fma_f32 v[4:5], v[182:183], v[152:153], v[4:5] op_sel_hi:[1,0,1]
	v_pk_fma_f32 v[10:11], v[180:181], v[152:153], v[10:11] op_sel:[0,1,0]
	v_pk_fma_f32 v[12:13], v[182:183], v[152:153], v[12:13] op_sel:[0,1,0]
	v_pk_fma_f32 v[14:15], v[180:181], v[154:155], v[14:15] op_sel_hi:[1,0,1]
	v_pk_fma_f32 v[16:17], v[182:183], v[154:155], v[16:17] op_sel_hi:[1,0,1]
	v_pk_fma_f32 v[6:7], v[180:181], v[154:155], v[6:7] op_sel:[0,1,0]
	v_pk_fma_f32 v[8:9], v[182:183], v[154:155], v[8:9] op_sel:[0,1,0]
	v_pk_fma_f32 v[18:19], v[180:181], v[156:157], v[18:19] op_sel_hi:[1,0,1]
	v_pk_fma_f32 v[20:21], v[182:183], v[156:157], v[20:21] op_sel_hi:[1,0,1]
	v_pk_fma_f32 v[26:27], v[180:181], v[156:157], v[26:27] op_sel:[0,1,0]
	v_pk_fma_f32 v[28:29], v[182:183], v[156:157], v[28:29] op_sel:[0,1,0]
	v_pk_fma_f32 v[30:31], v[180:181], v[158:159], v[30:31] op_sel_hi:[1,0,1]
	v_pk_fma_f32 v[32:33], v[182:183], v[158:159], v[32:33] op_sel_hi:[1,0,1]
	v_pk_fma_f32 v[22:23], v[180:181], v[158:159], v[22:23] op_sel:[0,1,0]
	v_pk_fma_f32 v[24:25], v[182:183], v[158:159], v[24:25] op_sel:[0,1,0]
	s_waitcnt lgkmcnt(0)
	ds_read_b128 v[152:155], v78 offset:1888
	ds_read_b128 v[156:159], v78 offset:1904
	s_waitcnt vmcnt(5)
	v_pk_fma_f32 v[2:3], v[184:185], v[144:145], v[2:3] op_sel_hi:[1,0,1]
	v_pk_fma_f32 v[4:5], v[186:187], v[144:145], v[4:5] op_sel_hi:[1,0,1]
	v_pk_fma_f32 v[10:11], v[184:185], v[144:145], v[10:11] op_sel:[0,1,0]
	v_pk_fma_f32 v[12:13], v[186:187], v[144:145], v[12:13] op_sel:[0,1,0]
	v_pk_fma_f32 v[14:15], v[184:185], v[146:147], v[14:15] op_sel_hi:[1,0,1]
	v_pk_fma_f32 v[16:17], v[186:187], v[146:147], v[16:17] op_sel_hi:[1,0,1]
	v_pk_fma_f32 v[6:7], v[184:185], v[146:147], v[6:7] op_sel:[0,1,0]
	v_pk_fma_f32 v[8:9], v[186:187], v[146:147], v[8:9] op_sel:[0,1,0]
	v_pk_fma_f32 v[18:19], v[184:185], v[148:149], v[18:19] op_sel_hi:[1,0,1]
	v_pk_fma_f32 v[20:21], v[186:187], v[148:149], v[20:21] op_sel_hi:[1,0,1]
	v_pk_fma_f32 v[26:27], v[184:185], v[148:149], v[26:27] op_sel:[0,1,0]
	v_pk_fma_f32 v[28:29], v[186:187], v[148:149], v[28:29] op_sel:[0,1,0]
	v_pk_fma_f32 v[30:31], v[184:185], v[150:151], v[30:31] op_sel_hi:[1,0,1]
	v_pk_fma_f32 v[32:33], v[186:187], v[150:151], v[32:33] op_sel_hi:[1,0,1]
	v_pk_fma_f32 v[22:23], v[184:185], v[150:151], v[22:23] op_sel:[0,1,0]
	v_pk_fma_f32 v[24:25], v[186:187], v[150:151], v[24:25] op_sel:[0,1,0]
	s_waitcnt lgkmcnt(0)
	ds_read_b128 v[144:147], v78 offset:1920
	ds_read_b128 v[148:151], v78 offset:1936
	s_waitcnt vmcnt(4)
; #define LAS __attribute__((address_space(3)))
; __device__ __forceinline__ void mod_item(int item, const float* w_ada, const float* b_ada, float* mod, LAS unsigned char* lds, int tid) {
;     ...
;     for (int kk = 0; kk < 64; ++kk) {
;         const f32x4 w = *(const f32x4*)(wp + (size_t)kk * 6144);
;         const f32x4 c0 = *(const LAS f32x4*)(cond + (ks * 64 + kk) * 8), c1 = *(const LAS f32x4*)(cond + (ks * 64 + kk) * 8 + 4);
;         a0 += c0[0] * w; a1 += c0[1] * w; a2 += c0[2] * w; a3 += c0[3] * w; a4 += c1[0] * w; a5 += c1[1] * w; a6 += c1[2] * w; a7 += c1[3] * w;
;     }
;     LAS float* rp = red + (ks * 8) * 64 + quad * 4;
;     *(LAS f32x4*)(rp + 0 * 64) = a0; *(LAS f32x4*)(rp + 1 * 64) = a1; *(LAS f32x4*)(rp + 2 * 64) = a2; *(LAS f32x4*)(rp + 3 * 64) = a3;
;     *(LAS f32x4*)(rp + 4 * 64) = a4; *(LAS f32x4*)(rp + 5 * 64) = a5; *(LAS f32x4*)(rp + 6 * 64) = a6; *(LAS f32x4*)(rp + 7 * 64) = a7;
;     __syncthreads();
	v_pk_fma_f32 v[2:3], v[188:189], v[152:153], v[2:3] op_sel_hi:[1,0,1]
	v_pk_fma_f32 v[4:5], v[190:191], v[152:153], v[4:5] op_sel_hi:[1,0,1]
	v_pk_fma_f32 v[10:11], v[188:189], v[152:153], v[10:11] op_sel:[0,1,0]
	v_pk_fma_f32 v[12:13], v[190:191], v[152:153], v[12:13] op_sel:[0,1,0]
	v_pk_fma_f32 v[14:15], v[188:189], v[154:155], v[14:15] op_sel_hi:[1,0,1]
	v_pk_fma_f32 v[16:17], v[190:191], v[154:155], v[16:17] op_sel_hi:[1,0,1]
	v_pk_fma_f32 v[6:7], v[188:189], v[154:155], v[6:7] op_sel:[0,1,0]
	v_pk_fma_f32 v[8:9], v[190:191], v[154:155], v[8:9] op_sel:[0,1,0]
	v_pk_fma_f32 v[18:19], v[188:189], v[156:157], v[18:19] op_sel_hi:[1,0,1]
	v_pk_fma_f32 v[20:21], v[190:191], v[156:157], v[20:21] op_sel_hi:[1,0,1]
	v_pk_fma_f32 v[26:27], v[188:189], v[156:157], v[26:27] op_sel:[0,1,0]
	v_pk_fma_f32 v[28:29], v[190:191], v[156:157], v[28:29] op_sel:[0,1,0]
	v_pk_fma_f32 v[30:31], v[188:189], v[158:159], v[30:31] op_sel_hi:[1,0,1]
	v_pk_fma_f32 v[32:33], v[190:191], v[158:159], v[32:33] op_sel_hi:[1,0,1]
	v_pk_fma_f32 v[22:23], v[188:189], v[158:159], v[22:23] op_sel:[0,1,0]
	v_pk_fma_f32 v[24:25], v[190:191], v[158:159], v[24:25] op_sel:[0,1,0]
	s_waitcnt lgkmcnt(0)
	ds_read_b128 v[152:155], v78 offset:1952
	ds_read_b128 v[156:159], v78 offset:1968
	s_waitcnt vmcnt(3)
	v_pk_fma_f32 v[2:3], v[192:193], v[144:145], v[2:3] op_sel_hi:[1,0,1]
	v_pk_fma_f32 v[4:5], v[194:195], v[144:145], v[4:5] op_sel_hi:[1,0,1]
	v_pk_fma_f32 v[10:11], v[192:193], v[144:145], v[10:11] op_sel:[0,1,0]
	v_pk_fma_f32 v[12:13], v[194:195], v[144:145], v[12:13] op_sel:[0,1,0]
	v_pk_fma_f32 v[14:15], v[192:193], v[146:147], v[14:15] op_sel_hi:[1,0,1]
	v_pk_fma_f32 v[16:17], v[194:195], v[146:147], v[16:17] op_sel_hi:[1,0,1]
	v_pk_fma_f32 v[6:7], v[192:193], v[146:147], v[6:7] op_sel:[0,1,0]
	v_pk_fma_f32 v[8:9], v[194:195], v[146:147], v[8:9] op_sel:[0,1,0]
	v_pk_fma_f32 v[18:19], v[192:193], v[148:149], v[18:19] op_sel_hi:[1,0,1]
	v_pk_fma_f32 v[20:21], v[194:195], v[148:149], v[20:21] op_sel_hi:[1,0,1]
	v_pk_fma_f32 v[26:27], v[192:193], v[148:149], v[26:27] op_sel:[0,1,0]
	v_pk_fma_f32 v[28:29], v[194:195], v[148:149], v[28:29] op_sel:[0,1,0]
	v_pk_fma_f32 v[30:31], v[192:193], v[150:151], v[30:31] op_sel_hi:[1,0,1]
	v_pk_fma_f32 v[32:33], v[194:195], v[150:151], v[32:33] op_sel_hi:[1,0,1]
	v_pk_fma_f32 v[22:23], v[192:193], v[150:151], v[22:23] op_sel:[0,1,0]
	v_pk_fma_f32 v[24:25], v[194:195], v[150:151], v[24:25] op_sel:[0,1,0]
	s_waitcnt lgkmcnt(0)
	ds_read_b128 v[144:147], v78 offset:1984
	ds_read_b128 v[148:151], v78 offset:2000
	s_waitcnt vmcnt(2)
	v_pk_fma_f32 v[2:3], v[196:197], v[152:153], v[2:3] op_sel_hi:[1,0,1]
	v_pk_fma_f32 v[4:5], v[198:199], v[152:153], v[4:5] op_sel_hi:[1,0,1]
	v_pk_fma_f32 v[10:11], v[196:197], v[152:153], v[10:11] op_sel:[0,1,0]
	v_pk_fma_f32 v[12:13], v[198:199], v[152:153], v[12:13] op_sel:[0,1,0]
	v_pk_fma_f32 v[14:15], v[196:197], v[154:155], v[14:15] op_sel_hi:[1,0,1]
	v_pk_fma_f32 v[16:17], v[198:199], v[154:155], v[16:17] op_sel_hi:[1,0,1]
	v_pk_fma_f32 v[6:7], v[196:197], v[154:155], v[6:7] op_sel:[0,1,0]
	v_pk_fma_f32 v[8:9], v[198:199], v[154:155], v[8:9] op_sel:[0,1,0]
	v_pk_fma_f32 v[18:19], v[196:197], v[156:157], v[18:19] op_sel_hi:[1,0,1]
	v_pk_fma_f32 v[20:21], v[198:199], v[156:157], v[20:21] op_sel_hi:[1,0,1]
	v_pk_fma_f32 v[26:27], v[196:197], v[156:157], v[26:27] op_sel:[0,1,0]
	v_pk_fma_f32 v[28:29], v[198:199], v[156:157], v[28:29] op_sel:[0,1,0]
	v_pk_fma_f32 v[30:31], v[196:197], v[158:159], v[30:31] op_sel_hi:[1,0,1]
	v_pk_fma_f32 v[32:33], v[198:199], v[158:159], v[32:33] op_sel_hi:[1,0,1]
	v_pk_fma_f32 v[22:23], v[196:197], v[158:159], v[22:23] op_sel:[0,1,0]
	v_pk_fma_f32 v[24:25], v[198:199], v[158:159], v[24:25] op_sel:[0,1,0]
	s_waitcnt lgkmcnt(0)
	ds_read_b128 v[152:155], v78 offset:2016
	ds_read_b128 v[156:159], v78 offset:2032
	s_waitcnt vmcnt(1)
	v_pk_fma_f32 v[2:3], v[200:201], v[144:145], v[2:3] op_sel_hi:[1,0,1]
	v_pk_fma_f32 v[4:5], v[202:203], v[144:145], v[4:5] op_sel_hi:[1,0,1]
	v_pk_fma_f32 v[10:11], v[200:201], v[144:145], v[10:11] op_sel:[0,1,0]
	v_pk_fma_f32 v[12:13], v[202:203], v[144:145], v[12:13] op_sel:[0,1,0]
	v_pk_fma_f32 v[14:15], v[200:201], v[146:147], v[14:15] op_sel_hi:[1,0,1]
	v_pk_fma_f32 v[16:17], v[202:203], v[146:147], v[16:17] op_sel_hi:[1,0,1]
	v_pk_fma_f32 v[6:7], v[200:201], v[146:147], v[6:7] op_sel:[0,1,0]
	v_pk_fma_f32 v[8:9], v[202:203], v[146:147], v[8:9] op_sel:[0,1,0]
	v_pk_fma_f32 v[18:19], v[200:201], v[148:149], v[18:19] op_sel_hi:[1,0,1]
	v_pk_fma_f32 v[20:21], v[202:203], v[148:149], v[20:21] op_sel_hi:[1,0,1]
	v_pk_fma_f32 v[26:27], v[200:201], v[148:149], v[26:27] op_sel:[0,1,0]
	v_pk_fma_f32 v[28:29], v[202:203], v[148:149], v[28:29] op_sel:[0,1,0]
	v_pk_fma_f32 v[30:31], v[200:201], v[150:151], v[30:31] op_sel_hi:[1,0,1]
	v_pk_fma_f32 v[32:33], v[202:203], v[150:151], v[32:33] op_sel_hi:[1,0,1]
	v_pk_fma_f32 v[22:23], v[200:201], v[150:151], v[22:23] op_sel:[0,1,0]
	v_pk_fma_f32 v[24:25], v[202:203], v[150:151], v[24:25] op_sel:[0,1,0]
	s_waitcnt lgkmcnt(0)
	s_waitcnt vmcnt(0)
	v_pk_fma_f32 v[2:3], v[204:205], v[152:153], v[2:3] op_sel_hi:[1,0,1]
	v_pk_fma_f32 v[4:5], v[206:207], v[152:153], v[4:5] op_sel_hi:[1,0,1]
	v_pk_fma_f32 v[10:11], v[204:205], v[152:153], v[10:11] op_sel:[0,1,0]
	v_pk_fma_f32 v[12:13], v[206:207], v[152:153], v[12:13] op_sel:[0,1,0]
	v_pk_fma_f32 v[14:15], v[204:205], v[154:155], v[14:15] op_sel_hi:[1,0,1]
	v_pk_fma_f32 v[16:17], v[206:207], v[154:155], v[16:17] op_sel_hi:[1,0,1]
	v_pk_fma_f32 v[6:7], v[204:205], v[154:155], v[6:7] op_sel:[0,1,0]
	v_pk_fma_f32 v[8:9], v[206:207], v[154:155], v[8:9] op_sel:[0,1,0]
	v_pk_fma_f32 v[18:19], v[204:205], v[156:157], v[18:19] op_sel_hi:[1,0,1]
	v_pk_fma_f32 v[20:21], v[206:207], v[156:157], v[20:21] op_sel_hi:[1,0,1]
	v_pk_fma_f32 v[26:27], v[204:205], v[156:157], v[26:27] op_sel:[0,1,0]
	v_pk_fma_f32 v[28:29], v[206:207], v[156:157], v[28:29] op_sel:[0,1,0]
	v_pk_fma_f32 v[30:31], v[204:205], v[158:159], v[30:31] op_sel_hi:[1,0,1]
	v_pk_fma_f32 v[32:33], v[206:207], v[158:159], v[32:33] op_sel_hi:[1,0,1]
	v_pk_fma_f32 v[22:23], v[204:205], v[158:159], v[22:23] op_sel:[0,1,0]
	v_pk_fma_f32 v[24:25], v[206:207], v[158:159], v[24:25] op_sel:[0,1,0]
	ds_write_b128 v1, v[2:5]
	ds_write_b128 v1, v[10:13] offset:256
	ds_write_b128 v1, v[14:17] offset:512
	ds_write_b128 v1, v[6:9] offset:768
	ds_write_b128 v1, v[18:21] offset:1024
	ds_write_b128 v1, v[26:29] offset:1280
	ds_write_b128 v1, v[30:33] offset:1536
	ds_write_b128 v1, v[22:25] offset:1792
	v_mov_b32_e32 v2, 0
	s_mov_b32 s14, 0
	s_waitcnt lgkmcnt(0)
	s_barrier

.LBB0_458:
	s_waitcnt vmcnt(3)
	ds_write_b128 v243, v[112:115]
	s_waitcnt vmcnt(2)
	ds_write_b128 v243, v[116:119] offset:9216
	v_add_u32_e32 v112, s17, v242
	v_add_u32_e32 v177, s16, v246
	s_waitcnt vmcnt(1)
	ds_write_b128 v112, v[120:123] offset:36864
	s_waitcnt vmcnt(0)
	ds_write_b128 v112, v[124:127] offset:47104
	s_waitcnt lgkmcnt(11)
	v_mfma_f32_32x32x16_bf16 v[128:143], v[220:223], v[156:159], v[64:79]
	v_add_f32_e32 v112, v96, v98
	v_add_f32_e32 v113, v97, v99
	v_add_f32_e32 v112, v100, v112
	v_add_f32_e32 v113, v101, v113
	v_cvt_pk_bf16_f32 v160, v96, v97
	v_cvt_pk_bf16_f32 v161, v98, v99
	s_nop 0
	v_add_f32_e32 v96, v102, v112
	v_add_f32_e32 v97, v103, v113
	s_waitcnt lgkmcnt(9)
	v_mfma_f32_32x32x16_bf16 v[112:127], v[216:219], v[156:159], v[64:79]
	v_add_f32_e32 v96, v104, v96
	v_add_f32_e32 v97, v105, v97
	v_cvt_pk_bf16_f32 v162, v100, v101
	v_cvt_pk_bf16_f32 v163, v102, v103
	v_mfma_f32_32x32x16_bf16 v[128:143], v[212:215], v[152:155], v[128:143]
	v_add_f32_e32 v96, v106, v96
	v_add_f32_e32 v97, v107, v97
	v_add_f32_e32 v96, v108, v96
	v_add_f32_e32 v97, v109, v97
	v_cvt_pk_bf16_f32 v164, v104, v105
	v_cvt_pk_bf16_f32 v165, v106, v107
	s_waitcnt lgkmcnt(8)
	v_mfma_f32_32x32x16_bf16 v[112:127], v[208:211], v[152:155], v[112:127]
	v_add_f32_e32 v96, v110, v96
	v_add_f32_e32 v97, v111, v97
	v_add_f32_e32 v96, v80, v96
	v_add_f32_e32 v97, v81, v97
	v_cvt_pk_bf16_f32 v166, v108, v109
	v_cvt_pk_bf16_f32 v167, v110, v111
	s_waitcnt lgkmcnt(7)
	v_mfma_f32_32x32x16_bf16 v[128:143], v[204:207], v[148:151], v[128:143]
	ds_read_b64_tr_b16 v[220:221], v177 offset:36864
	ds_read_b64_tr_b16 v[222:223], v177 offset:39424
	v_add_f32_e32 v96, v82, v96
	v_add_f32_e32 v97, v83, v97
	v_add_f32_e32 v96, v84, v96
	v_add_f32_e32 v97, v85, v97
	v_cvt_pk_bf16_f32 v168, v80, v81
	v_cvt_pk_bf16_f32 v169, v82, v83
	s_waitcnt lgkmcnt(7)
	v_mfma_f32_32x32x16_bf16 v[112:127], v[200:203], v[148:151], v[112:127]
	ds_read_b64_tr_b16 v[108:109], v177 offset:36928
	ds_read_b64_tr_b16 v[110:111], v177 offset:39488
	v_add_f32_e32 v80, v86, v96
	v_add_f32_e32 v81, v87, v97
	v_add_f32_e32 v80, v88, v80
	v_add_f32_e32 v81, v89, v81
	v_cvt_pk_bf16_f32 v170, v84, v85
	v_cvt_pk_bf16_f32 v171, v86, v87
	v_mfma_f32_32x32x16_bf16 v[128:143], v[196:199], v[144:147], v[128:143]
	ds_read_b64_tr_b16 v[104:105], v177 offset:36992
	ds_read_b64_tr_b16 v[106:107], v177 offset:39552
	v_add_f32_e32 v80, v90, v80
	v_add_f32_e32 v81, v91, v81
	v_add_f32_e32 v80, v92, v80
	v_add_f32_e32 v81, v93, v81
	v_cvt_pk_bf16_f32 v172, v88, v89
	v_cvt_pk_bf16_f32 v173, v90, v91
	s_waitcnt lgkmcnt(10)
	v_mfma_f32_32x32x16_bf16 v[112:127], v[192:195], v[144:147], v[112:127]
	ds_read_b64_tr_b16 v[100:101], v177 offset:37056
	ds_read_b64_tr_b16 v[102:103], v177 offset:39616
	v_add_f32_e32 v80, v94, v80
	v_add_f32_e32 v81, v95, v81
	v_add_f32_e32 v80, 0, v80
	v_add_f32_e32 v81, 0, v81
	v_cvt_pk_bf16_f32 v174, v92, v93
	v_cvt_pk_bf16_f32 v175, v94, v95
	s_nop 0
	v_add_f32_e32 v80, v80, v81
	s_nop 3
	v_add_f32_e32 v247, v247, v80
	v_max3_f32 v81, v128, v129, v112
	v_max3_f32 v82, v130, v131, v113
	v_max3_f32 v81, v81, v114, v115
	v_max3_f32 v82, v82, v134, v135
	v_max3_f32 v81, v81, v132, v133
	v_max3_f32 v82, v82, v118, v119
	v_max3_f32 v81, v81, v116, v117
	v_max3_f32 v82, v82, v138, v139
	v_max3_f32 v81, v81, v136, v137
	v_max3_f32 v82, v82, v122, v123
	v_max3_f32 v81, v81, v120, v121
	v_max3_f32 v82, v82, v142, v143
	v_max3_f32 v81, v81, v140, v141
	v_max3_f32 v82, v82, v126, v127
	v_max3_f32 v81, v81, v124, v125
	v_max_f32_e32 v80, v81, v82
	v_mov_b32_e32 v81, v80
	s_nop 1
	v_permlane32_swap_b32_e32 v80, v81
	v_max_f32_e32 v80, v80, v81
	v_cmp_lt_f32_e32 vcc, s61, v80
	s_cbranch_vccnz .LBB0_466
	v_mov_b32_e32 v176, 1.0

.LBB0_462:
	s_add_i32 s18, s16, 0x5000
	s_cmpk_lg_u32 s16, 0xf000
	s_cselect_b32 s16, s18, 0
	s_add_i32 s18, s17, 0x5000
	s_cmpk_lg_u32 s17, 0xf000
	s_cselect_b32 s17, s18, 0
	s_waitcnt vmcnt(3)
	ds_write_b128 v243, v[80:83] offset:18432
	s_waitcnt vmcnt(2)
	ds_write_b128 v243, v[84:87] offset:27648
	v_add_u32_e32 v80, s17, v242
	v_add_u32_e32 v161, s16, v246
	s_waitcnt vmcnt(1)
	ds_write_b128 v80, v[88:91] offset:36864
	s_waitcnt vmcnt(0)
	ds_write_b128 v80, v[96:99] offset:47104
	v_mfma_f32_32x32x16_bf16 v[96:111], v[92:95], v[156:159], v[64:79]
	v_add_f32_e32 v80, v128, v130
	v_add_f32_e32 v81, v129, v131
	v_add_f32_e32 v80, v132, v80
	v_add_f32_e32 v81, v133, v81
	v_cvt_pk_bf16_f32 v176, v128, v129
	v_cvt_pk_bf16_f32 v177, v130, v131
	s_nop 0
	v_add_f32_e32 v80, v134, v80
	v_add_f32_e32 v81, v135, v81
	v_add_f32_e32 v128, v136, v80
	v_add_f32_e32 v129, v137, v81
	v_mfma_f32_32x32x16_bf16 v[80:95], v[216:219], v[156:159], v[64:79]
	v_cvt_pk_bf16_f32 v178, v132, v133
	v_cvt_pk_bf16_f32 v179, v134, v135
	v_mfma_f32_32x32x16_bf16 v[96:111], v[212:215], v[152:155], v[96:111]
	v_add_f32_e32 v128, v138, v128
	v_add_f32_e32 v129, v139, v129
	v_add_f32_e32 v128, v140, v128
	v_add_f32_e32 v129, v141, v129
	v_cvt_pk_bf16_f32 v180, v136, v137
	v_cvt_pk_bf16_f32 v181, v138, v139
	v_mfma_f32_32x32x16_bf16 v[80:95], v[208:211], v[152:155], v[80:95]
	v_add_f32_e32 v128, v142, v128
	v_add_f32_e32 v129, v143, v129
	v_add_f32_e32 v128, v112, v128
	v_add_f32_e32 v129, v113, v129
	v_cvt_pk_bf16_f32 v182, v140, v141
	v_cvt_pk_bf16_f32 v183, v142, v143
	v_mfma_f32_32x32x16_bf16 v[96:111], v[204:207], v[148:151], v[96:111]
	ds_read_b64_tr_b16 v[140:141], v161 offset:36864
	ds_read_b64_tr_b16 v[142:143], v161 offset:39424
	v_add_f32_e32 v128, v114, v128
	v_add_f32_e32 v129, v115, v129
	v_add_f32_e32 v128, v116, v128
	v_add_f32_e32 v129, v117, v129
	v_cvt_pk_bf16_f32 v184, v112, v113
	v_cvt_pk_bf16_f32 v185, v114, v115
	v_mfma_f32_32x32x16_bf16 v[80:95], v[200:203], v[148:151], v[80:95]
	ds_read_b64_tr_b16 v[136:137], v161 offset:36928
	ds_read_b64_tr_b16 v[138:139], v161 offset:39488
	v_add_f32_e32 v112, v118, v128
	v_add_f32_e32 v113, v119, v129
	v_add_f32_e32 v112, v120, v112
	v_add_f32_e32 v113, v121, v113
	v_cvt_pk_bf16_f32 v186, v116, v117
	v_cvt_pk_bf16_f32 v187, v118, v119
	v_mfma_f32_32x32x16_bf16 v[96:111], v[196:199], v[144:147], v[96:111]
	ds_read_b64_tr_b16 v[132:133], v161 offset:36992
	ds_read_b64_tr_b16 v[134:135], v161 offset:39552
	v_add_f32_e32 v112, v122, v112
	v_add_f32_e32 v113, v123, v113
	v_add_f32_e32 v112, v124, v112
	v_add_f32_e32 v113, v125, v113
	v_cvt_pk_bf16_f32 v188, v120, v121
	v_cvt_pk_bf16_f32 v189, v122, v123
	v_mfma_f32_32x32x16_bf16 v[80:95], v[192:195], v[144:147], v[80:95]
	ds_read_b64_tr_b16 v[128:129], v161 offset:37056
	ds_read_b64_tr_b16 v[130:131], v161 offset:39616
	v_add_f32_e32 v112, v126, v112
	v_add_f32_e32 v113, v127, v113
	v_add_f32_e32 v112, 0, v112
	v_add_f32_e32 v113, 0, v113
	v_cvt_pk_bf16_f32 v190, v124, v125
	v_cvt_pk_bf16_f32 v191, v126, v127
	s_nop 0
	v_add_f32_e32 v112, v112, v113
	s_nop 3
	v_add_f32_e32 v247, v247, v112
	v_max3_f32 v113, v96, v97, v80
	v_max3_f32 v114, v98, v99, v81
	v_max3_f32 v113, v113, v82, v83
	v_max3_f32 v114, v114, v102, v103
	v_max3_f32 v113, v113, v100, v101
	v_max3_f32 v114, v114, v86, v87
	v_max3_f32 v113, v113, v84, v85
	v_max3_f32 v114, v114, v106, v107
	v_max3_f32 v113, v113, v104, v105
	v_max3_f32 v114, v114, v90, v91
	v_max3_f32 v113, v113, v88, v89
	v_max3_f32 v114, v114, v110, v111
	v_max3_f32 v113, v113, v108, v109
	v_max3_f32 v114, v114, v94, v95
	v_max3_f32 v113, v113, v92, v93
	v_max_f32_e32 v112, v113, v114
	v_mov_b32_e32 v113, v112
	s_nop 1
	v_permlane32_swap_b32_e32 v112, v113
	v_max_f32_e32 v112, v112, v113
	v_cmp_lt_f32_e32 vcc, s61, v112
	s_cbranch_vccnz .LBB0_467
	v_mov_b32_e32 v160, 1.0

.LBB0_468:
	s_waitcnt vmcnt(3)
	v_or_b32_e32 v112, 0x9000, v245
	v_add_u32_e32 v160, 0, v112
	s_waitcnt vmcnt(0)
	v_mfma_f32_32x32x16_bf16 v[112:127], v[220:223], v[156:159], v[64:79]
	v_add_f32_e32 v128, v96, v98
	v_add_f32_e32 v129, v97, v99
	v_add_f32_e32 v132, v100, v128
	v_add_f32_e32 v133, v101, v129
	v_cvt_pk_bf16_f32 v128, v96, v97
	v_cvt_pk_bf16_f32 v129, v98, v99
	v_mfma_f32_32x32x16_bf16 v[64:79], v[216:219], v[156:159], v[64:79]
	v_add_f32_e32 v96, v102, v132
	v_add_f32_e32 v97, v103, v133
	v_add_f32_e32 v96, v104, v96
	v_add_f32_e32 v97, v105, v97
	v_cvt_pk_bf16_f32 v130, v100, v101
	v_cvt_pk_bf16_f32 v131, v102, v103
	v_mfma_f32_32x32x16_bf16 v[112:127], v[212:215], v[152:155], v[112:127]
	v_add_f32_e32 v96, v106, v96
	v_add_f32_e32 v97, v107, v97
	v_add_f32_e32 v96, v108, v96
	v_add_f32_e32 v97, v109, v97
	v_cvt_pk_bf16_f32 v104, v104, v105
	v_cvt_pk_bf16_f32 v105, v106, v107
	v_mfma_f32_32x32x16_bf16 v[64:79], v[208:211], v[152:155], v[64:79]
	v_add_f32_e32 v96, v110, v96
	v_add_f32_e32 v97, v111, v97
	v_add_f32_e32 v96, v80, v96
	v_add_f32_e32 v97, v81, v97
	v_cvt_pk_bf16_f32 v106, v108, v109
	v_cvt_pk_bf16_f32 v107, v110, v111
	v_mfma_f32_32x32x16_bf16 v[112:127], v[204:207], v[148:151], v[112:127]
	ds_read_b64_tr_b16 v[140:141], v160 offset:40960
	ds_read_b64_tr_b16 v[142:143], v160 offset:43520
	v_add_f32_e32 v96, v82, v96
	v_add_f32_e32 v97, v83, v97
	v_add_f32_e32 v96, v84, v96
	v_add_f32_e32 v97, v85, v97
	v_cvt_pk_bf16_f32 v100, v80, v81
	v_cvt_pk_bf16_f32 v101, v82, v83
	v_mfma_f32_32x32x16_bf16 v[64:79], v[200:203], v[148:151], v[64:79]
	ds_read_b64_tr_b16 v[136:137], v160 offset:41024
	ds_read_b64_tr_b16 v[138:139], v160 offset:43584
	v_add_f32_e32 v80, v86, v96
	v_add_f32_e32 v81, v87, v97
	v_add_f32_e32 v80, v88, v80
	v_add_f32_e32 v81, v89, v81
	v_cvt_pk_bf16_f32 v102, v84, v85
	v_cvt_pk_bf16_f32 v103, v86, v87
	v_mfma_f32_32x32x16_bf16 v[112:127], v[196:199], v[144:147], v[112:127]
	ds_read_b64_tr_b16 v[132:133], v160 offset:41088
	ds_read_b64_tr_b16 v[134:135], v160 offset:43648
	v_add_f32_e32 v80, v90, v80
	v_add_f32_e32 v81, v91, v81
	v_add_f32_e32 v80, v92, v80
	v_add_f32_e32 v81, v93, v81
	v_cvt_pk_bf16_f32 v96, v88, v89
	v_cvt_pk_bf16_f32 v97, v90, v91
	v_mfma_f32_32x32x16_bf16 v[64:79], v[192:195], v[144:147], v[64:79]
	ds_read_b64_tr_b16 v[108:109], v160 offset:41152
	ds_read_b64_tr_b16 v[110:111], v160 offset:43712
	v_add_f32_e32 v80, v94, v80
	v_add_f32_e32 v81, v95, v81
	v_add_f32_e32 v80, 0, v80
	v_add_f32_e32 v81, 0, v81
	v_cvt_pk_bf16_f32 v98, v92, v93
	v_cvt_pk_bf16_f32 v99, v94, v95
	s_nop 0
	v_add_f32_e32 v80, v80, v81
	s_nop 3
	v_add_f32_e32 v145, v247, v80
	v_max3_f32 v81, v112, v113, v64
	v_max3_f32 v82, v114, v115, v65
	v_max3_f32 v81, v81, v66, v67
	v_max3_f32 v82, v82, v118, v119
	v_max3_f32 v81, v81, v116, v117
	v_max3_f32 v82, v82, v70, v71
	v_max3_f32 v81, v81, v68, v69
	v_max3_f32 v82, v82, v122, v123
	v_max3_f32 v81, v81, v120, v121
	v_max3_f32 v82, v82, v74, v75
	v_max3_f32 v81, v81, v72, v73
	v_max3_f32 v82, v82, v126, v127
	v_max3_f32 v81, v81, v124, v125
	v_max3_f32 v82, v82, v78, v79
	v_max3_f32 v81, v81, v76, v77
	v_max_f32_e32 v80, v81, v82
	v_mov_b32_e32 v81, v80
	s_nop 1
	v_permlane32_swap_b32_e32 v80, v81
	v_max_f32_e32 v80, v80, v81
	v_cmp_lt_f32_e32 vcc, s61, v80
	s_cbranch_vccnz .LBB0_472
	v_mov_b32_e32 v144, 1.0
